# GEMM load segments: pending ds_read_b128 moved into the M0 -> LDS-DMA wait-state slots (62 s_nop removed)
# speedup vs baseline: 1.0042x; 1.0042x over previous
; #define PG8_STAGE(bufoff, gbase, voff) do { _Pragma("unroll") for (int _i = 0; _i < 2; ++_i) \
;         __builtin_amdgcn_global_load_lds((const unsigned*)((const char*)(gbase) + (voff)[_i]), (PG8_LAS unsigned*)(lds + (bufoff) + ldsw + _i * 8192), 16, 0, 0); } while (0)
; #define PG8_LDA(dst, b, h) do { _Pragma("unroll") for (int m = 0; m < 4; ++m) _Pragma("unroll") for (int k = 0; k < 2; ++k) dst[m][k] = *(const PG8_LAS bf16x8*)(lds + PG8_SA(b, h) + aoff + m * 2048 + k * 1024); } while (0)
; #define PG8_LDB(dst, b, h) do { _Pragma("unroll") for (int n = 0; n < 2; ++n) _Pragma("unroll") for (int k = 0; k < 2; ++k) dst[n][k] = *(const PG8_LAS bf16x8*)(lds + PG8_SB(b, h) + boff + n * 2048 + k * 1024); } while (0)
; #define PG8_MMA(ai, bj, At, Bt) do { __builtin_amdgcn_s_setprio(1); _Pragma("unroll") for (int m = 0; m < 4; ++m) _Pragma("unroll") for (int n = 0; n < 2; ++n) _Pragma("unroll") for (int k = 0; k < 2; ++k) \
;         acc[ai][bj][m][n] = __builtin_amdgcn_mfma_f32_16x16x32_bf16(Bt[n][k], At[m][k], acc[ai][bj][m][n], 0, 0, 0); __builtin_amdgcn_s_setprio(0); } while (0)
; #define PG8_WAIT_V(n) asm volatile("s_waitcnt vmcnt(" #n ")" ::: "memory")
; #define PG8_WAIT_L(n) asm volatile("s_waitcnt lgkmcnt(" #n ")" ::: "memory")
; template <class Epi, class Sched, bool ALIGN_EPI = false, bool SP2 = false>
; __device__ __forceinline__ void gemm_phase(PG8_LAS unsigned char* lds, const Gemm g, const Sched& S, const Epi& E, int tid_in) {
;     ...
;             const bool last = (t == nt - 2);
;             const char* a1 = cA + (size_t)(t + 1) * kstep;
;             const char* a2 = last ? nA : cA + (size_t)(t + 2) * kstep; const char* b2 = last ? nB : cB + (size_t)(t + 2) * kstep;
;             const char* a3 = a2 + kstep; const char* b3 = b2 + kstep;
;             if (last && has_next) S.a_ready(nxt);
;             if constexpr (SP2) {
;             PG8_LDB(B0, 0, 0); PG8_LDB(B1, 0, 1); PG8_SCHED; PG8_LDA(At, 0, 0); PG8_STAGE(PG8_SA(1, 1), a1 + hstepA, voffA);
;             PG8_WAIT_V(8); PG8_WAIT_L(0); PG8_BAR; PG8_MMA(0, 0, At, B0); PG8_MMA(0, 1, At, B1); PG8_BAR; PG8_SCHED;
;             PG8_LDA(At, 0, 1); PG8_STAGE(PG8_SB(0, 0), b2, voffB); PG8_STAGE(PG8_SB(0, 1), b2 + hstep, voffB); PG8_STAGE(PG8_SA(0, 0), a2, voffA);
;             PG8_WAIT_V(8); PG8_WAIT_L(0); PG8_BAR; PG8_MMA(1, 0, At, B0); PG8_MMA(1, 1, At, B1); PG8_BAR; PG8_SCHED;
.LBB0_204:
	s_add_u32 s10, s2, 0xfffc0080
	s_addc_u32 s11, s3, -1
	s_add_i32 s28, 0, 0x10000
	s_cmp_eq_u32 s27, 12
	s_cselect_b32 s13, s15, s11
	s_cselect_b32 s12, s20, s10
	v_add_u32_e32 v156, s28, v159
	s_cselect_b32 s11, s21, s26
	s_cselect_b32 s10, s24, s25
	s_add_i32 s52, 0, 0x14000
	ds_read_b128 v[144:147], v156
	ds_read_b128 v[148:151], v156 offset:1024
	ds_read_b128 v[152:155], v156 offset:2048
	ds_read_b128 v[162:165], v156 offset:3072
	v_add_u32_e32 v156, s52, v159
	ds_read_b128 v[166:169], v156
	ds_read_b128 v[170:173], v156 offset:1024
	ds_read_b128 v[174:177], v156 offset:2048
	ds_read_b128 v[178:181], v156 offset:3072
	s_add_i32 m0, s35, 0xc000
	ds_read_b128 v[182:185], v160
	ds_read_b128 v[186:189], v160 offset:1024
	ds_read_b128 v[200:203], v160 offset:2048
	ds_read_b128 v[204:207], v160 offset:3072
	ds_read_b128 v[208:211], v160 offset:4096
	ds_read_b128 v[212:215], v160 offset:5120
	ds_read_b128 v[216:219], v160 offset:6144
	global_load_lds_dwordx4 v142, s[2:3]
	s_add_i32 m0, s35, 0xe000
	ds_read_b128 v[226:229], v160 offset:7168
	global_load_lds_dwordx4 v140, s[2:3]
	s_waitcnt vmcnt(8)
	s_waitcnt lgkmcnt(0)
	s_barrier
	s_setprio 1
	s_waitcnt lgkmcnt(0)
	v_mfma_f32_16x16x32_bf16 v[124:127], v[144:147], v[182:185], v[124:127]
	v_mfma_f32_16x16x32_bf16 v[120:123], v[152:155], v[182:185], v[120:123]
	v_mfma_f32_16x16x32_bf16 v[108:111], v[144:147], v[200:203], v[108:111]
	v_mfma_f32_16x16x32_bf16 v[104:107], v[152:155], v[200:203], v[104:107]
	v_mfma_f32_16x16x32_bf16 v[92:95], v[144:147], v[208:211], v[92:95]
	v_mfma_f32_16x16x32_bf16 v[88:91], v[152:155], v[208:211], v[88:91]
	v_mfma_f32_16x16x32_bf16 v[76:79], v[144:147], v[216:219], v[76:79]
	v_mfma_f32_16x16x32_bf16 v[72:75], v[152:155], v[216:219], v[72:75]
	v_mfma_f32_16x16x32_bf16 v[124:127], v[148:151], v[186:189], v[124:127]
	v_mfma_f32_16x16x32_bf16 v[120:123], v[162:165], v[186:189], v[120:123]
	v_mfma_f32_16x16x32_bf16 v[108:111], v[148:151], v[204:207], v[108:111]
	v_mfma_f32_16x16x32_bf16 v[104:107], v[162:165], v[204:207], v[104:107]
	v_mfma_f32_16x16x32_bf16 v[92:95], v[148:151], v[212:215], v[92:95]
	v_mfma_f32_16x16x32_bf16 v[88:91], v[162:165], v[212:215], v[88:91]
	v_mfma_f32_16x16x32_bf16 v[76:79], v[148:151], v[226:229], v[76:79]
	v_mfma_f32_16x16x32_bf16 v[72:75], v[162:165], v[226:229], v[72:75]
	s_setprio 0
	s_setprio 1
	v_mfma_f32_16x16x32_bf16 v[116:119], v[166:169], v[182:185], v[116:119]
	v_mfma_f32_16x16x32_bf16 v[112:115], v[174:177], v[182:185], v[112:115]
	v_mfma_f32_16x16x32_bf16 v[100:103], v[166:169], v[200:203], v[100:103]
	v_mfma_f32_16x16x32_bf16 v[96:99], v[174:177], v[200:203], v[96:99]
	v_mfma_f32_16x16x32_bf16 v[84:87], v[166:169], v[208:211], v[84:87]
	v_mfma_f32_16x16x32_bf16 v[80:83], v[174:177], v[208:211], v[80:83]
	v_mfma_f32_16x16x32_bf16 v[68:71], v[166:169], v[216:219], v[68:71]
	v_mfma_f32_16x16x32_bf16 v[64:67], v[174:177], v[216:219], v[64:67]
	v_mfma_f32_16x16x32_bf16 v[116:119], v[170:173], v[186:189], v[116:119]
	v_mfma_f32_16x16x32_bf16 v[112:115], v[178:181], v[186:189], v[112:115]
	v_mfma_f32_16x16x32_bf16 v[100:103], v[170:173], v[204:207], v[100:103]
	v_mfma_f32_16x16x32_bf16 v[96:99], v[178:181], v[204:207], v[96:99]
	v_mfma_f32_16x16x32_bf16 v[84:87], v[170:173], v[212:215], v[84:87]
	v_mfma_f32_16x16x32_bf16 v[80:83], v[178:181], v[212:215], v[80:83]
	v_mfma_f32_16x16x32_bf16 v[68:71], v[170:173], v[226:229], v[68:71]
	v_mfma_f32_16x16x32_bf16 v[64:67], v[178:181], v[226:229], v[64:67]
	s_setprio 0
	s_barrier
	s_add_i32 s28, s28, s34
	s_mov_b32 m0, s28
	ds_read_b128 v[182:185], v160 offset:16384
	ds_read_b128 v[186:189], v160 offset:17408
	ds_read_b128 v[200:203], v160 offset:18432
	ds_read_b128 v[204:207], v160 offset:19456
	ds_read_b128 v[208:211], v160 offset:20480
	global_load_lds_dwordx4 v132, s[10:11]
	s_add_i32 m0, s28, 0x2000
	s_add_u32 s28, s10, 0x40000
	s_addc_u32 s29, s11, 0
	s_add_i32 s52, s52, s34
	global_load_lds_dwordx4 v128, s[10:11]
	s_mov_b32 m0, s52
	s_mov_b64 s[100:101], s[12:13]
	global_load_lds_dwordx4 v132, s[28:29]
	s_add_i32 m0, s52, 0x2000
	ds_read_b128 v[212:215], v160 offset:21504
	global_load_lds_dwordx4 v128, s[28:29]
	s_mov_b32 m0, s35
	ds_read_b128 v[216:219], v160 offset:22528
	global_load_lds_dwordx4 v134, s[100:101]
	s_mov_b32 m0, s38
	ds_read_b128 v[226:229], v160 offset:23552
	global_load_lds_dwordx4 v130, s[100:101]
	s_waitcnt vmcnt(8)
	s_waitcnt lgkmcnt(0)
	s_barrier
	s_setprio 1
	s_waitcnt lgkmcnt(0)
	v_mfma_f32_16x16x32_bf16 v[60:63], v[144:147], v[182:185], v[60:63]
	v_mfma_f32_16x16x32_bf16 v[56:59], v[152:155], v[182:185], v[56:59]
	v_mfma_f32_16x16x32_bf16 v[44:47], v[144:147], v[200:203], v[44:47]
	v_mfma_f32_16x16x32_bf16 v[40:43], v[152:155], v[200:203], v[40:43]
	v_mfma_f32_16x16x32_bf16 v[28:31], v[144:147], v[208:211], v[28:31]
	v_mfma_f32_16x16x32_bf16 v[24:27], v[152:155], v[208:211], v[24:27]
	v_mfma_f32_16x16x32_bf16 v[12:15], v[144:147], v[216:219], v[12:15]
	v_mfma_f32_16x16x32_bf16 v[8:11], v[152:155], v[216:219], v[8:11]
	v_mfma_f32_16x16x32_bf16 v[60:63], v[148:151], v[186:189], v[60:63]
	v_mfma_f32_16x16x32_bf16 v[56:59], v[162:165], v[186:189], v[56:59]
	v_mfma_f32_16x16x32_bf16 v[44:47], v[148:151], v[204:207], v[44:47]
	v_mfma_f32_16x16x32_bf16 v[40:43], v[162:165], v[204:207], v[40:43]
	v_mfma_f32_16x16x32_bf16 v[28:31], v[148:151], v[212:215], v[28:31]
	v_mfma_f32_16x16x32_bf16 v[24:27], v[162:165], v[212:215], v[24:27]
	v_mfma_f32_16x16x32_bf16 v[12:15], v[148:151], v[226:229], v[12:15]
	v_mfma_f32_16x16x32_bf16 v[8:11], v[162:165], v[226:229], v[8:11]
	s_setprio 0
	s_setprio 1
	v_mfma_f32_16x16x32_bf16 v[52:55], v[166:169], v[182:185], v[52:55]
	v_mfma_f32_16x16x32_bf16 v[48:51], v[174:177], v[182:185], v[48:51]
	v_mfma_f32_16x16x32_bf16 v[36:39], v[166:169], v[200:203], v[36:39]
	v_mfma_f32_16x16x32_bf16 v[32:35], v[174:177], v[200:203], v[32:35]
	v_mfma_f32_16x16x32_bf16 v[20:23], v[166:169], v[208:211], v[20:23]
	v_mfma_f32_16x16x32_bf16 v[16:19], v[174:177], v[208:211], v[16:19]
	v_mfma_f32_16x16x32_bf16 v[4:7], v[166:169], v[216:219], v[4:7]
	v_mfma_f32_16x16x32_bf16 v[0:3], v[174:177], v[216:219], v[0:3]
	v_mfma_f32_16x16x32_bf16 v[52:55], v[170:173], v[186:189], v[52:55]
	v_mfma_f32_16x16x32_bf16 v[48:51], v[178:181], v[186:189], v[48:51]
	v_mfma_f32_16x16x32_bf16 v[36:39], v[170:173], v[204:207], v[36:39]
	v_mfma_f32_16x16x32_bf16 v[32:35], v[178:181], v[204:207], v[32:35]
	v_mfma_f32_16x16x32_bf16 v[20:23], v[170:173], v[212:215], v[20:23]
	v_mfma_f32_16x16x32_bf16 v[16:19], v[178:181], v[212:215], v[16:19]
	v_mfma_f32_16x16x32_bf16 v[4:7], v[170:173], v[226:229], v[4:7]
	v_mfma_f32_16x16x32_bf16 v[0:3], v[178:181], v[226:229], v[0:3]
	s_setprio 0
	s_barrier
; #define PG8_STAGE(bufoff, gbase, voff) do { _Pragma("unroll") for (int _i = 0; _i < 2; ++_i) \
;         __builtin_amdgcn_global_load_lds((const unsigned*)((const char*)(gbase) + (voff)[_i]), (PG8_LAS unsigned*)(lds + (bufoff) + ldsw + _i * 8192), 16, 0, 0); } while (0)
; #define PG8_LDA(dst, b, h) do { _Pragma("unroll") for (int m = 0; m < 4; ++m) _Pragma("unroll") for (int k = 0; k < 2; ++k) dst[m][k] = *(const PG8_LAS bf16x8*)(lds + PG8_SA(b, h) + aoff + m * 2048 + k * 1024); } while (0)
; #define PG8_LDB(dst, b, h) do { _Pragma("unroll") for (int n = 0; n < 2; ++n) _Pragma("unroll") for (int k = 0; k < 2; ++k) dst[n][k] = *(const PG8_LAS bf16x8*)(lds + PG8_SB(b, h) + boff + n * 2048 + k * 1024); } while (0)
; #define PG8_MMA(ai, bj, At, Bt) do { __builtin_amdgcn_s_setprio(1); _Pragma("unroll") for (int m = 0; m < 4; ++m) _Pragma("unroll") for (int n = 0; n < 2; ++n) _Pragma("unroll") for (int k = 0; k < 2; ++k) \
;         acc[ai][bj][m][n] = __builtin_amdgcn_mfma_f32_16x16x32_bf16(Bt[n][k], At[m][k], acc[ai][bj][m][n], 0, 0, 0); __builtin_amdgcn_s_setprio(0); } while (0)
; #define PG8_WAIT_V(n) asm volatile("s_waitcnt vmcnt(" #n ")" ::: "memory")
; #define PG8_WAIT_L(n) asm volatile("s_waitcnt lgkmcnt(" #n ")" ::: "memory")
; #define PG8_BAR __builtin_amdgcn_s_barrier()
; #define PG8_SCHED __builtin_amdgcn_sched_barrier(0)
; template <class Epi, class Sched, bool ALIGN_EPI = false, bool SP2 = false>
; __device__ __forceinline__ void gemm_phase(PG8_LAS unsigned char* lds, const Gemm g, const Sched& S, const Epi& E, int tid_in) {
;     ...
;             PG8_LDB(B0, 1, 0); PG8_LDB(B1, 1, 1); PG8_SCHED; PG8_LDA(At, 1, 0); PG8_STAGE(PG8_SA(0, 1), a2 + hstepA, voffA);
;             PG8_WAIT_V(8); PG8_WAIT_L(0); PG8_BAR; PG8_MMA(0, 0, At, B0); PG8_MMA(0, 1, At, B1); PG8_BAR; PG8_SCHED;
;             PG8_LDA(At, 1, 1); PG8_STAGE(PG8_SB(1, 0), b3, voffB); PG8_STAGE(PG8_SB(1, 1), b3 + hstep, voffB); PG8_STAGE(PG8_SA(1, 0), a3, voffA);
;             PG8_WAIT_V(8); PG8_WAIT_L(0); PG8_BAR; PG8_MMA(1, 0, At, B0); PG8_MMA(1, 1, At, B1); PG8_BAR; PG8_SCHED;
;     ...
;         if constexpr (ALIGN_EPI) { if (wr == 0) PG8_BAR; }
	s_add_i32 s28, 0, 0x18000
	v_add_u32_e32 v161, s28, v159
	s_add_i32 s29, 0, 0x1c000
	ds_read_b128 v[144:147], v161
	ds_read_b128 v[148:151], v161 offset:1024
	ds_read_b128 v[152:155], v161 offset:2048
	ds_read_b128 v[162:165], v161 offset:3072
	v_add_u32_e32 v161, s29, v159
	ds_read_b128 v[166:169], v161
	ds_read_b128 v[170:173], v161 offset:1024
	ds_read_b128 v[174:177], v161 offset:2048
	ds_read_b128 v[178:181], v161 offset:3072
	s_add_u32 s12, s12, 0x40000
	s_addc_u32 s13, s13, 0
	s_mov_b32 m0, s77
	ds_read_b128 v[182:185], v160 offset:32768
	ds_read_b128 v[186:189], v160 offset:33792
	ds_read_b128 v[200:203], v160 offset:34816
	ds_read_b128 v[204:207], v160 offset:35840
	ds_read_b128 v[208:211], v160 offset:36864
	ds_read_b128 v[212:215], v160 offset:37888
	ds_read_b128 v[216:219], v160 offset:38912
	global_load_lds_dwordx4 v134, s[12:13]
	s_mov_b32 m0, s78
	ds_read_b128 v[226:229], v160 offset:39936
	global_load_lds_dwordx4 v130, s[12:13]
	s_waitcnt vmcnt(8)
	s_waitcnt lgkmcnt(0)
	s_barrier
	s_setprio 1
	s_waitcnt lgkmcnt(0)
	v_mfma_f32_16x16x32_bf16 v[124:127], v[144:147], v[182:185], v[124:127]
	v_mfma_f32_16x16x32_bf16 v[120:123], v[152:155], v[182:185], v[120:123]
	v_mfma_f32_16x16x32_bf16 v[108:111], v[144:147], v[200:203], v[108:111]
	v_mfma_f32_16x16x32_bf16 v[104:107], v[152:155], v[200:203], v[104:107]
	v_mfma_f32_16x16x32_bf16 v[92:95], v[144:147], v[208:211], v[92:95]
	v_mfma_f32_16x16x32_bf16 v[88:91], v[152:155], v[208:211], v[88:91]
	v_mfma_f32_16x16x32_bf16 v[76:79], v[144:147], v[216:219], v[76:79]
	v_mfma_f32_16x16x32_bf16 v[72:75], v[152:155], v[216:219], v[72:75]
	v_mfma_f32_16x16x32_bf16 v[124:127], v[148:151], v[186:189], v[124:127]
	v_mfma_f32_16x16x32_bf16 v[120:123], v[162:165], v[186:189], v[120:123]
	v_mfma_f32_16x16x32_bf16 v[108:111], v[148:151], v[204:207], v[108:111]
	v_mfma_f32_16x16x32_bf16 v[104:107], v[162:165], v[204:207], v[104:107]
	v_mfma_f32_16x16x32_bf16 v[92:95], v[148:151], v[212:215], v[92:95]
	v_mfma_f32_16x16x32_bf16 v[88:91], v[162:165], v[212:215], v[88:91]
	v_mfma_f32_16x16x32_bf16 v[76:79], v[148:151], v[226:229], v[76:79]
	v_mfma_f32_16x16x32_bf16 v[72:75], v[162:165], v[226:229], v[72:75]
	s_setprio 0
	s_setprio 1
	v_mfma_f32_16x16x32_bf16 v[116:119], v[166:169], v[182:185], v[116:119]
	v_mfma_f32_16x16x32_bf16 v[112:115], v[174:177], v[182:185], v[112:115]
	v_mfma_f32_16x16x32_bf16 v[100:103], v[166:169], v[200:203], v[100:103]
	v_mfma_f32_16x16x32_bf16 v[96:99], v[174:177], v[200:203], v[96:99]
	v_mfma_f32_16x16x32_bf16 v[84:87], v[166:169], v[208:211], v[84:87]
	v_mfma_f32_16x16x32_bf16 v[80:83], v[174:177], v[208:211], v[80:83]
	v_mfma_f32_16x16x32_bf16 v[68:71], v[166:169], v[216:219], v[68:71]
	v_mfma_f32_16x16x32_bf16 v[64:67], v[174:177], v[216:219], v[64:67]
	v_mfma_f32_16x16x32_bf16 v[116:119], v[170:173], v[186:189], v[116:119]
	v_mfma_f32_16x16x32_bf16 v[112:115], v[178:181], v[186:189], v[112:115]
	v_mfma_f32_16x16x32_bf16 v[100:103], v[170:173], v[204:207], v[100:103]
	v_mfma_f32_16x16x32_bf16 v[96:99], v[178:181], v[204:207], v[96:99]
	v_mfma_f32_16x16x32_bf16 v[84:87], v[170:173], v[212:215], v[84:87]
	v_mfma_f32_16x16x32_bf16 v[80:83], v[178:181], v[212:215], v[80:83]
	v_mfma_f32_16x16x32_bf16 v[68:71], v[170:173], v[226:229], v[68:71]
	v_mfma_f32_16x16x32_bf16 v[64:67], v[178:181], v[226:229], v[64:67]
	s_setprio 0
	s_barrier
	s_add_i32 s12, s28, s34
	s_mov_b32 m0, s12
	ds_read_b128 v[182:185], v160 offset:49152
	ds_read_b128 v[186:189], v160 offset:50176
	ds_read_b128 v[200:203], v160 offset:51200
	ds_read_b128 v[204:207], v160 offset:52224
	s_add_u32 s10, s10, 0x80
	s_addc_u32 s11, s11, 0
	global_load_lds_dwordx4 v132, s[10:11]
	s_add_i32 m0, s12, 0x2000
	ds_read_b128 v[208:211], v160 offset:53248
	global_load_lds_dwordx4 v128, s[10:11]
	s_add_u32 s10, s10, 0x40000
	s_addc_u32 s11, s11, 0
	s_add_i32 s12, s29, s34
	s_mov_b32 m0, s12
	ds_read_b128 v[212:215], v160 offset:54272
	global_load_lds_dwordx4 v132, s[10:11]
	s_add_i32 m0, s12, 0x2000
	ds_read_b128 v[216:219], v160 offset:55296
	global_load_lds_dwordx4 v128, s[10:11]
	s_mov_b32 m0, s83
	s_nop 0
	s_add_u32 s100, s100, 0x80
	s_addc_u32 s101, s101, 0
	global_load_lds_dwordx4 v134, s[100:101]
	s_mov_b32 m0, s84
	ds_read_b128 v[226:229], v160 offset:56320
	global_load_lds_dwordx4 v130, s[100:101]
	s_waitcnt vmcnt(8)
	s_waitcnt lgkmcnt(0)
	s_barrier
	s_setprio 1
	s_waitcnt lgkmcnt(0)
	v_mfma_f32_16x16x32_bf16 v[60:63], v[144:147], v[182:185], v[60:63]
	v_mfma_f32_16x16x32_bf16 v[56:59], v[152:155], v[182:185], v[56:59]
	v_mfma_f32_16x16x32_bf16 v[44:47], v[144:147], v[200:203], v[44:47]
	v_mfma_f32_16x16x32_bf16 v[40:43], v[152:155], v[200:203], v[40:43]
	v_mfma_f32_16x16x32_bf16 v[28:31], v[144:147], v[208:211], v[28:31]
	v_mfma_f32_16x16x32_bf16 v[24:27], v[152:155], v[208:211], v[24:27]
	v_mfma_f32_16x16x32_bf16 v[12:15], v[144:147], v[216:219], v[12:15]
	v_mfma_f32_16x16x32_bf16 v[8:11], v[152:155], v[216:219], v[8:11]
	v_mfma_f32_16x16x32_bf16 v[60:63], v[148:151], v[186:189], v[60:63]
	v_mfma_f32_16x16x32_bf16 v[56:59], v[162:165], v[186:189], v[56:59]
	v_mfma_f32_16x16x32_bf16 v[44:47], v[148:151], v[204:207], v[44:47]
	v_mfma_f32_16x16x32_bf16 v[40:43], v[162:165], v[204:207], v[40:43]
	v_mfma_f32_16x16x32_bf16 v[28:31], v[148:151], v[212:215], v[28:31]
	v_mfma_f32_16x16x32_bf16 v[24:27], v[162:165], v[212:215], v[24:27]
	v_mfma_f32_16x16x32_bf16 v[12:15], v[148:151], v[226:229], v[12:15]
	v_mfma_f32_16x16x32_bf16 v[8:11], v[162:165], v[226:229], v[8:11]
	s_setprio 0
	s_setprio 1
	v_mfma_f32_16x16x32_bf16 v[52:55], v[166:169], v[182:185], v[52:55]
	v_mfma_f32_16x16x32_bf16 v[48:51], v[174:177], v[182:185], v[48:51]
	v_mfma_f32_16x16x32_bf16 v[36:39], v[166:169], v[200:203], v[36:39]
	v_mfma_f32_16x16x32_bf16 v[32:35], v[174:177], v[200:203], v[32:35]
	v_mfma_f32_16x16x32_bf16 v[20:23], v[166:169], v[208:211], v[20:23]
	v_mfma_f32_16x16x32_bf16 v[16:19], v[174:177], v[208:211], v[16:19]
	v_mfma_f32_16x16x32_bf16 v[4:7], v[166:169], v[216:219], v[4:7]
	v_mfma_f32_16x16x32_bf16 v[0:3], v[174:177], v[216:219], v[0:3]
	v_mfma_f32_16x16x32_bf16 v[52:55], v[170:173], v[186:189], v[52:55]
	v_mfma_f32_16x16x32_bf16 v[48:51], v[178:181], v[186:189], v[48:51]
	v_mfma_f32_16x16x32_bf16 v[36:39], v[170:173], v[204:207], v[36:39]
	v_mfma_f32_16x16x32_bf16 v[32:35], v[178:181], v[204:207], v[32:35]
	v_mfma_f32_16x16x32_bf16 v[20:23], v[170:173], v[212:215], v[20:23]
	v_mfma_f32_16x16x32_bf16 v[16:19], v[178:181], v[212:215], v[16:19]
	v_mfma_f32_16x16x32_bf16 v[4:7], v[170:173], v[226:229], v[4:7]
	v_mfma_f32_16x16x32_bf16 v[0:3], v[178:181], v[226:229], v[0:3]
	s_setprio 0
	s_barrier
	s_add_i32 s27, s27, 2
	s_add_u32 s25, s25, 0x100
	s_addc_u32 s26, s26, 0
	s_add_u32 s2, s2, 0x100
	s_addc_u32 s3, s3, 0
	s_cmp_gt_u32 s27, 13
	s_cbranch_scc0 .LBB0_204
	s_and_b64 vcc, exec, s[62:63]
	s_cbranch_vccz .LBB0_207
	s_barrier

; #define PG8_STAGE(bufoff, gbase, voff) do { _Pragma("unroll") for (int _i = 0; _i < 2; ++_i) \
;         __builtin_amdgcn_global_load_lds((const unsigned*)((const char*)(gbase) + (voff)[_i]), (PG8_LAS unsigned*)(lds + (bufoff) + ldsw + _i * 8192), 16, 0, 0); } while (0)
; #define PG8_LDA(dst, b, h) do { _Pragma("unroll") for (int m = 0; m < 4; ++m) _Pragma("unroll") for (int k = 0; k < 2; ++k) dst[m][k] = *(const PG8_LAS bf16x8*)(lds + PG8_SA(b, h) + aoff + m * 2048 + k * 1024); } while (0)
; #define PG8_LDB(dst, b, h) do { _Pragma("unroll") for (int n = 0; n < 2; ++n) _Pragma("unroll") for (int k = 0; k < 2; ++k) dst[n][k] = *(const PG8_LAS bf16x8*)(lds + PG8_SB(b, h) + boff + n * 2048 + k * 1024); } while (0)
; #define PG8_MMA(ai, bj, At, Bt) do { __builtin_amdgcn_s_setprio(1); _Pragma("unroll") for (int m = 0; m < 4; ++m) _Pragma("unroll") for (int n = 0; n < 2; ++n) _Pragma("unroll") for (int k = 0; k < 2; ++k) \
;         acc[ai][bj][m][n] = __builtin_amdgcn_mfma_f32_16x16x32_bf16(Bt[n][k], At[m][k], acc[ai][bj][m][n], 0, 0, 0); __builtin_amdgcn_s_setprio(0); } while (0)
; #define PG8_WAIT_V(n) asm volatile("s_waitcnt vmcnt(" #n ")" ::: "memory")
; #define PG8_WAIT_L(n) asm volatile("s_waitcnt lgkmcnt(" #n ")" ::: "memory")
; template <class Epi, class Sched, bool ALIGN_EPI = false, bool SP2 = false>
; __device__ __forceinline__ void gemm_phase(PG8_LAS unsigned char* lds, const Gemm g, const Sched& S, const Epi& E, int tid_in) {
;     ...
;             const bool last = (t == nt - 2);
;             const char* a1 = cA + (size_t)(t + 1) * kstep;
;             const char* a2 = last ? nA : cA + (size_t)(t + 2) * kstep; const char* b2 = last ? nB : cB + (size_t)(t + 2) * kstep;
;             const char* a3 = a2 + kstep; const char* b3 = b2 + kstep;
;             if (last && has_next) S.a_ready(nxt);
;             if constexpr (SP2) {
;             PG8_LDB(B0, 0, 0); PG8_LDB(B1, 0, 1); PG8_SCHED; PG8_LDA(At, 0, 0); PG8_STAGE(PG8_SA(1, 1), a1 + hstepA, voffA);
;             PG8_WAIT_V(8); PG8_WAIT_L(0); PG8_BAR; PG8_MMA(0, 0, At, B0); PG8_MMA(0, 1, At, B1); PG8_BAR; PG8_SCHED;
;             PG8_LDA(At, 0, 1); PG8_STAGE(PG8_SB(0, 0), b2, voffB); PG8_STAGE(PG8_SB(0, 1), b2 + hstep, voffB); PG8_STAGE(PG8_SA(0, 0), a2, voffA);
;             PG8_WAIT_V(8); PG8_WAIT_L(0); PG8_BAR; PG8_MMA(1, 0, At, B0); PG8_MMA(1, 1, At, B1); PG8_BAR; PG8_SCHED;
.LBB0_526:
	s_add_u32 s12, s2, 0xfffc0080
	s_addc_u32 s13, s3, -1
	s_add_i32 s66, 0, 0x10000
	s_cmp_eq_u32 s65, 12
	s_cselect_b32 s15, s45, s13
	s_cselect_b32 s14, s46, s12
	v_add_u32_e32 v148, s66, v151
	s_cselect_b32 s13, s29, s64
	s_cselect_b32 s12, s47, s51
	s_add_i32 s68, 0, 0x14000
	ds_read_b128 v[140:143], v148
	ds_read_b128 v[144:147], v148 offset:1024
	ds_read_b128 v[160:163], v148 offset:2048
	ds_read_b128 v[164:167], v148 offset:3072
	v_add_u32_e32 v148, s68, v151
	ds_read_b128 v[168:171], v148
	ds_read_b128 v[172:175], v148 offset:1024
	ds_read_b128 v[176:179], v148 offset:2048
	ds_read_b128 v[180:183], v148 offset:3072
	s_add_i32 m0, s56, 0xc000
	ds_read_b128 v[184:187], v156
	ds_read_b128 v[200:203], v156 offset:1024
	ds_read_b128 v[204:207], v156 offset:2048
	ds_read_b128 v[208:211], v156 offset:3072
	ds_read_b128 v[212:215], v156 offset:4096
	ds_read_b128 v[216:219], v156 offset:5120
	ds_read_b128 v[226:229], v156 offset:6144
	global_load_lds_dwordx4 v138, s[2:3]
	s_add_i32 m0, s56, 0xe000
	ds_read_b128 v[230:233], v156 offset:7168
	global_load_lds_dwordx4 v136, s[2:3]
	s_waitcnt vmcnt(8)
	s_waitcnt lgkmcnt(0)
	s_barrier
	s_setprio 1
	s_waitcnt lgkmcnt(0)
	v_mfma_f32_16x16x32_bf16 v[124:127], v[140:143], v[184:187], v[124:127]
	v_mfma_f32_16x16x32_bf16 v[120:123], v[160:163], v[184:187], v[120:123]
	v_mfma_f32_16x16x32_bf16 v[108:111], v[140:143], v[204:207], v[108:111]
	v_mfma_f32_16x16x32_bf16 v[104:107], v[160:163], v[204:207], v[104:107]
	v_mfma_f32_16x16x32_bf16 v[92:95], v[140:143], v[212:215], v[92:95]
	v_mfma_f32_16x16x32_bf16 v[88:91], v[160:163], v[212:215], v[88:91]
	v_mfma_f32_16x16x32_bf16 v[76:79], v[140:143], v[226:229], v[76:79]
	v_mfma_f32_16x16x32_bf16 v[72:75], v[160:163], v[226:229], v[72:75]
	v_mfma_f32_16x16x32_bf16 v[124:127], v[144:147], v[200:203], v[124:127]
	v_mfma_f32_16x16x32_bf16 v[120:123], v[164:167], v[200:203], v[120:123]
	v_mfma_f32_16x16x32_bf16 v[108:111], v[144:147], v[208:211], v[108:111]
	v_mfma_f32_16x16x32_bf16 v[104:107], v[164:167], v[208:211], v[104:107]
	v_mfma_f32_16x16x32_bf16 v[92:95], v[144:147], v[216:219], v[92:95]
	v_mfma_f32_16x16x32_bf16 v[88:91], v[164:167], v[216:219], v[88:91]
	v_mfma_f32_16x16x32_bf16 v[76:79], v[144:147], v[230:233], v[76:79]
	v_mfma_f32_16x16x32_bf16 v[72:75], v[164:167], v[230:233], v[72:75]
	s_setprio 0
	s_setprio 1
	v_mfma_f32_16x16x32_bf16 v[116:119], v[168:171], v[184:187], v[116:119]
	v_mfma_f32_16x16x32_bf16 v[112:115], v[176:179], v[184:187], v[112:115]
	v_mfma_f32_16x16x32_bf16 v[100:103], v[168:171], v[204:207], v[100:103]
	v_mfma_f32_16x16x32_bf16 v[96:99], v[176:179], v[204:207], v[96:99]
	v_mfma_f32_16x16x32_bf16 v[84:87], v[168:171], v[212:215], v[84:87]
	v_mfma_f32_16x16x32_bf16 v[80:83], v[176:179], v[212:215], v[80:83]
	v_mfma_f32_16x16x32_bf16 v[68:71], v[168:171], v[226:229], v[68:71]
	v_mfma_f32_16x16x32_bf16 v[64:67], v[176:179], v[226:229], v[64:67]
	v_mfma_f32_16x16x32_bf16 v[116:119], v[172:175], v[200:203], v[116:119]
	v_mfma_f32_16x16x32_bf16 v[112:115], v[180:183], v[200:203], v[112:115]
	v_mfma_f32_16x16x32_bf16 v[100:103], v[172:175], v[208:211], v[100:103]
	v_mfma_f32_16x16x32_bf16 v[96:99], v[180:183], v[208:211], v[96:99]
	v_mfma_f32_16x16x32_bf16 v[84:87], v[172:175], v[216:219], v[84:87]
	v_mfma_f32_16x16x32_bf16 v[80:83], v[180:183], v[216:219], v[80:83]
	v_mfma_f32_16x16x32_bf16 v[68:71], v[172:175], v[230:233], v[68:71]
	v_mfma_f32_16x16x32_bf16 v[64:67], v[180:183], v[230:233], v[64:67]
	s_setprio 0
	s_barrier
	s_add_i32 s66, s66, s49
	s_mov_b32 m0, s66
	ds_read_b128 v[184:187], v156 offset:16384
	ds_read_b128 v[200:203], v156 offset:17408
	ds_read_b128 v[204:207], v156 offset:18432
	ds_read_b128 v[208:211], v156 offset:19456
	ds_read_b128 v[212:215], v156 offset:20480
	global_load_lds_dwordx4 v132, s[12:13]
	s_add_i32 m0, s66, 0x2000
	s_add_u32 s66, s12, 0x40000
	s_addc_u32 s67, s13, 0
	s_add_i32 s68, s68, s49
	global_load_lds_dwordx4 v128, s[12:13]
	s_mov_b32 m0, s68
	s_mov_b64 s[100:101], s[14:15]
	global_load_lds_dwordx4 v132, s[66:67]
	s_add_i32 m0, s68, 0x2000
	ds_read_b128 v[216:219], v156 offset:21504
	global_load_lds_dwordx4 v128, s[66:67]
	s_mov_b32 m0, s56
	ds_read_b128 v[226:229], v156 offset:22528
	global_load_lds_dwordx4 v134, s[100:101]
	s_mov_b32 m0, s57
	ds_read_b128 v[230:233], v156 offset:23552
	global_load_lds_dwordx4 v130, s[100:101]
	s_waitcnt vmcnt(8)
	s_waitcnt lgkmcnt(0)
	s_barrier
	s_setprio 1
	s_waitcnt lgkmcnt(0)
	v_mfma_f32_16x16x32_bf16 v[60:63], v[140:143], v[184:187], v[60:63]
	v_mfma_f32_16x16x32_bf16 v[56:59], v[160:163], v[184:187], v[56:59]
	v_mfma_f32_16x16x32_bf16 v[44:47], v[140:143], v[204:207], v[44:47]
	v_mfma_f32_16x16x32_bf16 v[40:43], v[160:163], v[204:207], v[40:43]
	v_mfma_f32_16x16x32_bf16 v[28:31], v[140:143], v[212:215], v[28:31]
	v_mfma_f32_16x16x32_bf16 v[24:27], v[160:163], v[212:215], v[24:27]
	v_mfma_f32_16x16x32_bf16 v[12:15], v[140:143], v[226:229], v[12:15]
	v_mfma_f32_16x16x32_bf16 v[8:11], v[160:163], v[226:229], v[8:11]
	v_mfma_f32_16x16x32_bf16 v[60:63], v[144:147], v[200:203], v[60:63]
	v_mfma_f32_16x16x32_bf16 v[56:59], v[164:167], v[200:203], v[56:59]
	v_mfma_f32_16x16x32_bf16 v[44:47], v[144:147], v[208:211], v[44:47]
	v_mfma_f32_16x16x32_bf16 v[40:43], v[164:167], v[208:211], v[40:43]
	v_mfma_f32_16x16x32_bf16 v[28:31], v[144:147], v[216:219], v[28:31]
	v_mfma_f32_16x16x32_bf16 v[24:27], v[164:167], v[216:219], v[24:27]
	v_mfma_f32_16x16x32_bf16 v[12:15], v[144:147], v[230:233], v[12:15]
	v_mfma_f32_16x16x32_bf16 v[8:11], v[164:167], v[230:233], v[8:11]
	s_setprio 0
	s_setprio 1
	v_mfma_f32_16x16x32_bf16 v[52:55], v[168:171], v[184:187], v[52:55]
	v_mfma_f32_16x16x32_bf16 v[48:51], v[176:179], v[184:187], v[48:51]
	v_mfma_f32_16x16x32_bf16 v[36:39], v[168:171], v[204:207], v[36:39]
	v_mfma_f32_16x16x32_bf16 v[32:35], v[176:179], v[204:207], v[32:35]
	v_mfma_f32_16x16x32_bf16 v[20:23], v[168:171], v[212:215], v[20:23]
	v_mfma_f32_16x16x32_bf16 v[16:19], v[176:179], v[212:215], v[16:19]
	v_mfma_f32_16x16x32_bf16 v[4:7], v[168:171], v[226:229], v[4:7]
	v_mfma_f32_16x16x32_bf16 v[0:3], v[176:179], v[226:229], v[0:3]
	v_mfma_f32_16x16x32_bf16 v[52:55], v[172:175], v[200:203], v[52:55]
	v_mfma_f32_16x16x32_bf16 v[48:51], v[180:183], v[200:203], v[48:51]
	v_mfma_f32_16x16x32_bf16 v[36:39], v[172:175], v[208:211], v[36:39]
	v_mfma_f32_16x16x32_bf16 v[32:35], v[180:183], v[208:211], v[32:35]
	v_mfma_f32_16x16x32_bf16 v[20:23], v[172:175], v[216:219], v[20:23]
	v_mfma_f32_16x16x32_bf16 v[16:19], v[180:183], v[216:219], v[16:19]
	v_mfma_f32_16x16x32_bf16 v[4:7], v[172:175], v[230:233], v[4:7]
	v_mfma_f32_16x16x32_bf16 v[0:3], v[180:183], v[230:233], v[0:3]
	s_setprio 0
	s_barrier
; #define PG8_STAGE(bufoff, gbase, voff) do { _Pragma("unroll") for (int _i = 0; _i < 2; ++_i) \
;         __builtin_amdgcn_global_load_lds((const unsigned*)((const char*)(gbase) + (voff)[_i]), (PG8_LAS unsigned*)(lds + (bufoff) + ldsw + _i * 8192), 16, 0, 0); } while (0)
; #define PG8_LDA(dst, b, h) do { _Pragma("unroll") for (int m = 0; m < 4; ++m) _Pragma("unroll") for (int k = 0; k < 2; ++k) dst[m][k] = *(const PG8_LAS bf16x8*)(lds + PG8_SA(b, h) + aoff + m * 2048 + k * 1024); } while (0)
; #define PG8_LDB(dst, b, h) do { _Pragma("unroll") for (int n = 0; n < 2; ++n) _Pragma("unroll") for (int k = 0; k < 2; ++k) dst[n][k] = *(const PG8_LAS bf16x8*)(lds + PG8_SB(b, h) + boff + n * 2048 + k * 1024); } while (0)
; #define PG8_MMA(ai, bj, At, Bt) do { __builtin_amdgcn_s_setprio(1); _Pragma("unroll") for (int m = 0; m < 4; ++m) _Pragma("unroll") for (int n = 0; n < 2; ++n) _Pragma("unroll") for (int k = 0; k < 2; ++k) \
;         acc[ai][bj][m][n] = __builtin_amdgcn_mfma_f32_16x16x32_bf16(Bt[n][k], At[m][k], acc[ai][bj][m][n], 0, 0, 0); __builtin_amdgcn_s_setprio(0); } while (0)
; #define PG8_WAIT_V(n) asm volatile("s_waitcnt vmcnt(" #n ")" ::: "memory")
; #define PG8_WAIT_L(n) asm volatile("s_waitcnt lgkmcnt(" #n ")" ::: "memory")
; #define PG8_BAR __builtin_amdgcn_s_barrier()
; #define PG8_SCHED __builtin_amdgcn_sched_barrier(0)
; template <class Epi, class Sched, bool ALIGN_EPI = false, bool SP2 = false>
; __device__ __forceinline__ void gemm_phase(PG8_LAS unsigned char* lds, const Gemm g, const Sched& S, const Epi& E, int tid_in) {
;     ...
;             PG8_LDB(B0, 1, 0); PG8_LDB(B1, 1, 1); PG8_SCHED; PG8_LDA(At, 1, 0); PG8_STAGE(PG8_SA(0, 1), a2 + hstepA, voffA);
;             PG8_WAIT_V(8); PG8_WAIT_L(0); PG8_BAR; PG8_MMA(0, 0, At, B0); PG8_MMA(0, 1, At, B1); PG8_BAR; PG8_SCHED;
;             PG8_LDA(At, 1, 1); PG8_STAGE(PG8_SB(1, 0), b3, voffB); PG8_STAGE(PG8_SB(1, 1), b3 + hstep, voffB); PG8_STAGE(PG8_SA(1, 0), a3, voffA);
;             PG8_WAIT_V(8); PG8_WAIT_L(0); PG8_BAR; PG8_MMA(1, 0, At, B0); PG8_MMA(1, 1, At, B1); PG8_BAR; PG8_SCHED;
;     ...
;         if constexpr (ALIGN_EPI) { if (wr == 0) PG8_BAR; }
	s_add_i32 s66, 0, 0x18000
	v_add_u32_e32 v157, s66, v151
	s_add_i32 s67, 0, 0x1c000
	ds_read_b128 v[140:143], v157
	ds_read_b128 v[144:147], v157 offset:1024
	ds_read_b128 v[160:163], v157 offset:2048
	ds_read_b128 v[164:167], v157 offset:3072
	v_add_u32_e32 v157, s67, v151
	ds_read_b128 v[168:171], v157
	ds_read_b128 v[172:175], v157 offset:1024
	ds_read_b128 v[176:179], v157 offset:2048
	ds_read_b128 v[180:183], v157 offset:3072
	s_add_u32 s14, s14, 0x40000
	s_addc_u32 s15, s15, 0
	s_mov_b32 m0, s58
	ds_read_b128 v[184:187], v156 offset:32768
	ds_read_b128 v[200:203], v156 offset:33792
	ds_read_b128 v[204:207], v156 offset:34816
	ds_read_b128 v[208:211], v156 offset:35840
	ds_read_b128 v[212:215], v156 offset:36864
	ds_read_b128 v[216:219], v156 offset:37888
	ds_read_b128 v[226:229], v156 offset:38912
	global_load_lds_dwordx4 v134, s[14:15]
	s_mov_b32 m0, s59
	ds_read_b128 v[230:233], v156 offset:39936
	global_load_lds_dwordx4 v130, s[14:15]
	s_waitcnt vmcnt(8)
	s_waitcnt lgkmcnt(0)
	s_barrier
	s_setprio 1
	s_waitcnt lgkmcnt(0)
	v_mfma_f32_16x16x32_bf16 v[124:127], v[140:143], v[184:187], v[124:127]
	v_mfma_f32_16x16x32_bf16 v[120:123], v[160:163], v[184:187], v[120:123]
	v_mfma_f32_16x16x32_bf16 v[108:111], v[140:143], v[204:207], v[108:111]
	v_mfma_f32_16x16x32_bf16 v[104:107], v[160:163], v[204:207], v[104:107]
	v_mfma_f32_16x16x32_bf16 v[92:95], v[140:143], v[212:215], v[92:95]
	v_mfma_f32_16x16x32_bf16 v[88:91], v[160:163], v[212:215], v[88:91]
	v_mfma_f32_16x16x32_bf16 v[76:79], v[140:143], v[226:229], v[76:79]
	v_mfma_f32_16x16x32_bf16 v[72:75], v[160:163], v[226:229], v[72:75]
	v_mfma_f32_16x16x32_bf16 v[124:127], v[144:147], v[200:203], v[124:127]
	v_mfma_f32_16x16x32_bf16 v[120:123], v[164:167], v[200:203], v[120:123]
	v_mfma_f32_16x16x32_bf16 v[108:111], v[144:147], v[208:211], v[108:111]
	v_mfma_f32_16x16x32_bf16 v[104:107], v[164:167], v[208:211], v[104:107]
	v_mfma_f32_16x16x32_bf16 v[92:95], v[144:147], v[216:219], v[92:95]
	v_mfma_f32_16x16x32_bf16 v[88:91], v[164:167], v[216:219], v[88:91]
	v_mfma_f32_16x16x32_bf16 v[76:79], v[144:147], v[230:233], v[76:79]
	v_mfma_f32_16x16x32_bf16 v[72:75], v[164:167], v[230:233], v[72:75]
	s_setprio 0
	s_setprio 1
	v_mfma_f32_16x16x32_bf16 v[116:119], v[168:171], v[184:187], v[116:119]
	v_mfma_f32_16x16x32_bf16 v[112:115], v[176:179], v[184:187], v[112:115]
	v_mfma_f32_16x16x32_bf16 v[100:103], v[168:171], v[204:207], v[100:103]
	v_mfma_f32_16x16x32_bf16 v[96:99], v[176:179], v[204:207], v[96:99]
	v_mfma_f32_16x16x32_bf16 v[84:87], v[168:171], v[212:215], v[84:87]
	v_mfma_f32_16x16x32_bf16 v[80:83], v[176:179], v[212:215], v[80:83]
	v_mfma_f32_16x16x32_bf16 v[68:71], v[168:171], v[226:229], v[68:71]
	v_mfma_f32_16x16x32_bf16 v[64:67], v[176:179], v[226:229], v[64:67]
	v_mfma_f32_16x16x32_bf16 v[116:119], v[172:175], v[200:203], v[116:119]
	v_mfma_f32_16x16x32_bf16 v[112:115], v[180:183], v[200:203], v[112:115]
	v_mfma_f32_16x16x32_bf16 v[100:103], v[172:175], v[208:211], v[100:103]
	v_mfma_f32_16x16x32_bf16 v[96:99], v[180:183], v[208:211], v[96:99]
	v_mfma_f32_16x16x32_bf16 v[84:87], v[172:175], v[216:219], v[84:87]
	v_mfma_f32_16x16x32_bf16 v[80:83], v[180:183], v[216:219], v[80:83]
	v_mfma_f32_16x16x32_bf16 v[68:71], v[172:175], v[230:233], v[68:71]
	v_mfma_f32_16x16x32_bf16 v[64:67], v[180:183], v[230:233], v[64:67]
	s_setprio 0
	s_barrier
	s_add_i32 s14, s66, s49
	s_mov_b32 m0, s14
	ds_read_b128 v[184:187], v156 offset:49152
	ds_read_b128 v[200:203], v156 offset:50176
	ds_read_b128 v[204:207], v156 offset:51200
	ds_read_b128 v[208:211], v156 offset:52224
	s_add_u32 s12, s12, 0x80
	s_addc_u32 s13, s13, 0
	global_load_lds_dwordx4 v132, s[12:13]
	s_add_i32 m0, s14, 0x2000
	ds_read_b128 v[212:215], v156 offset:53248
	global_load_lds_dwordx4 v128, s[12:13]
	s_add_u32 s12, s12, 0x40000
	s_addc_u32 s13, s13, 0
	s_add_i32 s14, s67, s49
	s_mov_b32 m0, s14
	ds_read_b128 v[216:219], v156 offset:54272
	global_load_lds_dwordx4 v132, s[12:13]
	s_add_i32 m0, s14, 0x2000
	ds_read_b128 v[226:229], v156 offset:55296
	global_load_lds_dwordx4 v128, s[12:13]
	s_mov_b32 m0, s61
	s_nop 0
	s_add_u32 s100, s100, 0x80
	s_addc_u32 s101, s101, 0
	global_load_lds_dwordx4 v134, s[100:101]
	s_mov_b32 m0, s62
	ds_read_b128 v[230:233], v156 offset:56320
	global_load_lds_dwordx4 v130, s[100:101]
	s_waitcnt vmcnt(8)
	s_waitcnt lgkmcnt(0)
	s_barrier
	s_setprio 1
	s_waitcnt lgkmcnt(0)
	v_mfma_f32_16x16x32_bf16 v[60:63], v[140:143], v[184:187], v[60:63]
	v_mfma_f32_16x16x32_bf16 v[56:59], v[160:163], v[184:187], v[56:59]
	v_mfma_f32_16x16x32_bf16 v[44:47], v[140:143], v[204:207], v[44:47]
	v_mfma_f32_16x16x32_bf16 v[40:43], v[160:163], v[204:207], v[40:43]
	v_mfma_f32_16x16x32_bf16 v[28:31], v[140:143], v[212:215], v[28:31]
	v_mfma_f32_16x16x32_bf16 v[24:27], v[160:163], v[212:215], v[24:27]
	v_mfma_f32_16x16x32_bf16 v[12:15], v[140:143], v[226:229], v[12:15]
	v_mfma_f32_16x16x32_bf16 v[8:11], v[160:163], v[226:229], v[8:11]
	v_mfma_f32_16x16x32_bf16 v[60:63], v[144:147], v[200:203], v[60:63]
	v_mfma_f32_16x16x32_bf16 v[56:59], v[164:167], v[200:203], v[56:59]
	v_mfma_f32_16x16x32_bf16 v[44:47], v[144:147], v[208:211], v[44:47]
	v_mfma_f32_16x16x32_bf16 v[40:43], v[164:167], v[208:211], v[40:43]
	v_mfma_f32_16x16x32_bf16 v[28:31], v[144:147], v[216:219], v[28:31]
	v_mfma_f32_16x16x32_bf16 v[24:27], v[164:167], v[216:219], v[24:27]
	v_mfma_f32_16x16x32_bf16 v[12:15], v[144:147], v[230:233], v[12:15]
	v_mfma_f32_16x16x32_bf16 v[8:11], v[164:167], v[230:233], v[8:11]
	s_setprio 0
	s_setprio 1
	v_mfma_f32_16x16x32_bf16 v[52:55], v[168:171], v[184:187], v[52:55]
	v_mfma_f32_16x16x32_bf16 v[48:51], v[176:179], v[184:187], v[48:51]
	v_mfma_f32_16x16x32_bf16 v[36:39], v[168:171], v[204:207], v[36:39]
	v_mfma_f32_16x16x32_bf16 v[32:35], v[176:179], v[204:207], v[32:35]
	v_mfma_f32_16x16x32_bf16 v[20:23], v[168:171], v[212:215], v[20:23]
	v_mfma_f32_16x16x32_bf16 v[16:19], v[176:179], v[212:215], v[16:19]
	v_mfma_f32_16x16x32_bf16 v[4:7], v[168:171], v[226:229], v[4:7]
	v_mfma_f32_16x16x32_bf16 v[0:3], v[176:179], v[226:229], v[0:3]
	v_mfma_f32_16x16x32_bf16 v[52:55], v[172:175], v[200:203], v[52:55]
	v_mfma_f32_16x16x32_bf16 v[48:51], v[180:183], v[200:203], v[48:51]
	v_mfma_f32_16x16x32_bf16 v[36:39], v[172:175], v[208:211], v[36:39]
	v_mfma_f32_16x16x32_bf16 v[32:35], v[180:183], v[208:211], v[32:35]
	v_mfma_f32_16x16x32_bf16 v[20:23], v[172:175], v[216:219], v[20:23]
	v_mfma_f32_16x16x32_bf16 v[16:19], v[180:183], v[216:219], v[16:19]
	v_mfma_f32_16x16x32_bf16 v[4:7], v[172:175], v[230:233], v[4:7]
	v_mfma_f32_16x16x32_bf16 v[0:3], v[180:183], v[230:233], v[0:3]
	s_setprio 0
	s_barrier
	s_add_i32 s65, s65, 2
	s_add_u32 s51, s51, 0x100
	s_addc_u32 s64, s64, 0
	s_add_u32 s2, s2, 0x100
	s_addc_u32 s3, s3, 0
	s_cmp_gt_u32 s65, 13
	s_cbranch_scc0 .LBB0_526
	s_and_b64 vcc, exec, s[34:35]
	s_cbranch_vccz .LBB0_529
	s_barrier

; #define PG8_STAGE(bufoff, gbase, voff) do { _Pragma("unroll") for (int _i = 0; _i < 2; ++_i) \
;         __builtin_amdgcn_global_load_lds((const unsigned*)((const char*)(gbase) + (voff)[_i]), (PG8_LAS unsigned*)(lds + (bufoff) + ldsw + _i * 8192), 16, 0, 0); } while (0)
; #define PG8_LDA(dst, b, h) do { _Pragma("unroll") for (int m = 0; m < 4; ++m) _Pragma("unroll") for (int k = 0; k < 2; ++k) dst[m][k] = *(const PG8_LAS bf16x8*)(lds + PG8_SA(b, h) + aoff + m * 2048 + k * 1024); } while (0)
; #define PG8_LDB(dst, b, h) do { _Pragma("unroll") for (int n = 0; n < 2; ++n) _Pragma("unroll") for (int k = 0; k < 2; ++k) dst[n][k] = *(const PG8_LAS bf16x8*)(lds + PG8_SB(b, h) + boff + n * 2048 + k * 1024); } while (0)
; #define PG8_MMA(ai, bj, At, Bt) do { __builtin_amdgcn_s_setprio(1); _Pragma("unroll") for (int m = 0; m < 4; ++m) _Pragma("unroll") for (int n = 0; n < 2; ++n) _Pragma("unroll") for (int k = 0; k < 2; ++k) \
;         acc[ai][bj][m][n] = __builtin_amdgcn_mfma_f32_16x16x32_bf16(Bt[n][k], At[m][k], acc[ai][bj][m][n], 0, 0, 0); __builtin_amdgcn_s_setprio(0); } while (0)
; #define PG8_WAIT_V(n) asm volatile("s_waitcnt vmcnt(" #n ")" ::: "memory")
; #define PG8_WAIT_L(n) asm volatile("s_waitcnt lgkmcnt(" #n ")" ::: "memory")
; template <class Epi, class Sched, bool ALIGN_EPI = false, bool SP2 = false>
; __device__ __forceinline__ void gemm_phase(PG8_LAS unsigned char* lds, const Gemm g, const Sched& S, const Epi& E, int tid_in) {
;     ...
;             const bool last = (t == nt - 2);
;             const char* a1 = cA + (size_t)(t + 1) * kstep;
;             const char* a2 = last ? nA : cA + (size_t)(t + 2) * kstep; const char* b2 = last ? nB : cB + (size_t)(t + 2) * kstep;
;             const char* a3 = a2 + kstep; const char* b3 = b2 + kstep;
;             if (last && has_next) S.a_ready(nxt);
;             if constexpr (SP2) {
;             PG8_LDB(B0, 0, 0); PG8_LDB(B1, 0, 1); PG8_SCHED; PG8_LDA(At, 0, 0); PG8_STAGE(PG8_SA(1, 1), a1 + hstepA, voffA);
;             PG8_WAIT_V(8); PG8_WAIT_L(0); PG8_BAR; PG8_MMA(0, 0, At, B0); PG8_MMA(0, 1, At, B1); PG8_BAR; PG8_SCHED;
;             PG8_LDA(At, 0, 1); PG8_STAGE(PG8_SB(0, 0), b2, voffB); PG8_STAGE(PG8_SB(0, 1), b2 + hstep, voffB); PG8_STAGE(PG8_SA(0, 0), a2, voffA);
;             PG8_WAIT_V(8); PG8_WAIT_L(0); PG8_BAR; PG8_MMA(1, 0, At, B0); PG8_MMA(1, 1, At, B1); PG8_BAR; PG8_SCHED;
.LBB0_691:
	s_add_u32 s28, s26, 0xfffc0080
	s_addc_u32 s29, s27, -1
	s_add_i32 s57, 0, 0x10000
	s_cmp_eq_u32 s56, 12
	s_cselect_b32 s31, s15, s29
	s_cselect_b32 s30, s52, s28
	v_add_u32_e32 v147, s57, v145
	s_cselect_b32 s29, s13, s55
	s_cselect_b32 s28, s53, s54
	s_add_i32 s60, 0, 0x14000
	ds_read_b128 v[140:143], v147
	ds_read_b128 v[148:151], v147 offset:1024
	ds_read_b128 v[152:155], v147 offset:2048
	ds_read_b128 v[156:159], v147 offset:3072
	v_add_u32_e32 v147, s60, v145
	ds_read_b128 v[160:163], v147
	ds_read_b128 v[164:167], v147 offset:1024
	ds_read_b128 v[168:171], v147 offset:2048
	ds_read_b128 v[172:175], v147 offset:3072
	s_add_i32 m0, s42, 0xc000
	ds_read_b128 v[176:179], v146
	ds_read_b128 v[180:183], v146 offset:1024
	ds_read_b128 v[184:187], v146 offset:2048
	ds_read_b128 v[200:203], v146 offset:3072
	ds_read_b128 v[204:207], v146 offset:4096
	ds_read_b128 v[208:211], v146 offset:5120
	ds_read_b128 v[212:215], v146 offset:6144
	global_load_lds_dwordx4 v138, s[26:27]
	s_add_i32 m0, s42, 0xe000
	ds_read_b128 v[216:219], v146 offset:7168
	global_load_lds_dwordx4 v136, s[26:27]
	s_waitcnt vmcnt(8)
	s_waitcnt lgkmcnt(0)
	s_barrier
	s_setprio 1
	s_waitcnt lgkmcnt(0)
	v_mfma_f32_16x16x32_bf16 v[124:127], v[140:143], v[176:179], v[124:127]
	v_mfma_f32_16x16x32_bf16 v[120:123], v[152:155], v[176:179], v[120:123]
	v_mfma_f32_16x16x32_bf16 v[108:111], v[140:143], v[184:187], v[108:111]
	v_mfma_f32_16x16x32_bf16 v[104:107], v[152:155], v[184:187], v[104:107]
	v_mfma_f32_16x16x32_bf16 v[92:95], v[140:143], v[204:207], v[92:95]
	v_mfma_f32_16x16x32_bf16 v[88:91], v[152:155], v[204:207], v[88:91]
	v_mfma_f32_16x16x32_bf16 v[76:79], v[140:143], v[212:215], v[76:79]
	v_mfma_f32_16x16x32_bf16 v[72:75], v[152:155], v[212:215], v[72:75]
	v_mfma_f32_16x16x32_bf16 v[124:127], v[148:151], v[180:183], v[124:127]
	v_mfma_f32_16x16x32_bf16 v[120:123], v[156:159], v[180:183], v[120:123]
	v_mfma_f32_16x16x32_bf16 v[108:111], v[148:151], v[200:203], v[108:111]
	v_mfma_f32_16x16x32_bf16 v[104:107], v[156:159], v[200:203], v[104:107]
	v_mfma_f32_16x16x32_bf16 v[92:95], v[148:151], v[208:211], v[92:95]
	v_mfma_f32_16x16x32_bf16 v[88:91], v[156:159], v[208:211], v[88:91]
	v_mfma_f32_16x16x32_bf16 v[76:79], v[148:151], v[216:219], v[76:79]
	v_mfma_f32_16x16x32_bf16 v[72:75], v[156:159], v[216:219], v[72:75]
	s_setprio 0
	s_setprio 1
	v_mfma_f32_16x16x32_bf16 v[116:119], v[160:163], v[176:179], v[116:119]
	v_mfma_f32_16x16x32_bf16 v[112:115], v[168:171], v[176:179], v[112:115]
	v_mfma_f32_16x16x32_bf16 v[100:103], v[160:163], v[184:187], v[100:103]
	v_mfma_f32_16x16x32_bf16 v[96:99], v[168:171], v[184:187], v[96:99]
	v_mfma_f32_16x16x32_bf16 v[84:87], v[160:163], v[204:207], v[84:87]
	v_mfma_f32_16x16x32_bf16 v[80:83], v[168:171], v[204:207], v[80:83]
	v_mfma_f32_16x16x32_bf16 v[68:71], v[160:163], v[212:215], v[68:71]
	v_mfma_f32_16x16x32_bf16 v[64:67], v[168:171], v[212:215], v[64:67]
	v_mfma_f32_16x16x32_bf16 v[116:119], v[164:167], v[180:183], v[116:119]
	v_mfma_f32_16x16x32_bf16 v[112:115], v[172:175], v[180:183], v[112:115]
	v_mfma_f32_16x16x32_bf16 v[100:103], v[164:167], v[200:203], v[100:103]
	v_mfma_f32_16x16x32_bf16 v[96:99], v[172:175], v[200:203], v[96:99]
	v_mfma_f32_16x16x32_bf16 v[84:87], v[164:167], v[208:211], v[84:87]
	v_mfma_f32_16x16x32_bf16 v[80:83], v[172:175], v[208:211], v[80:83]
	v_mfma_f32_16x16x32_bf16 v[68:71], v[164:167], v[216:219], v[68:71]
	v_mfma_f32_16x16x32_bf16 v[64:67], v[172:175], v[216:219], v[64:67]
	s_setprio 0
	s_barrier
	s_add_i32 s57, s57, s41
	s_mov_b32 m0, s57
	ds_read_b128 v[176:179], v146 offset:16384
	ds_read_b128 v[180:183], v146 offset:17408
	ds_read_b128 v[184:187], v146 offset:18432
	ds_read_b128 v[200:203], v146 offset:19456
	ds_read_b128 v[204:207], v146 offset:20480
	global_load_lds_dwordx4 v132, s[28:29]
	s_add_i32 m0, s57, 0x2000
	s_add_u32 s58, s28, 0x40000
	s_addc_u32 s59, s29, 0
	s_add_i32 s57, s60, s41
	global_load_lds_dwordx4 v128, s[28:29]
	s_mov_b32 m0, s57
	s_mov_b64 s[100:101], s[30:31]
	global_load_lds_dwordx4 v132, s[58:59]
	s_add_i32 m0, s57, 0x2000
	ds_read_b128 v[208:211], v146 offset:21504
	global_load_lds_dwordx4 v128, s[58:59]
	s_mov_b32 m0, s42
	ds_read_b128 v[212:215], v146 offset:22528
	global_load_lds_dwordx4 v134, s[100:101]
	s_mov_b32 m0, s43
	ds_read_b128 v[216:219], v146 offset:23552
	global_load_lds_dwordx4 v130, s[100:101]
	s_waitcnt vmcnt(8)
	s_waitcnt lgkmcnt(0)
	s_barrier
	s_setprio 1
	s_waitcnt lgkmcnt(0)
	v_mfma_f32_16x16x32_bf16 v[60:63], v[140:143], v[176:179], v[60:63]
	v_mfma_f32_16x16x32_bf16 v[56:59], v[152:155], v[176:179], v[56:59]
	v_mfma_f32_16x16x32_bf16 v[44:47], v[140:143], v[184:187], v[44:47]
	v_mfma_f32_16x16x32_bf16 v[40:43], v[152:155], v[184:187], v[40:43]
	v_mfma_f32_16x16x32_bf16 v[28:31], v[140:143], v[204:207], v[28:31]
	v_mfma_f32_16x16x32_bf16 v[24:27], v[152:155], v[204:207], v[24:27]
	v_mfma_f32_16x16x32_bf16 v[12:15], v[140:143], v[212:215], v[12:15]
	v_mfma_f32_16x16x32_bf16 v[8:11], v[152:155], v[212:215], v[8:11]
	v_mfma_f32_16x16x32_bf16 v[60:63], v[148:151], v[180:183], v[60:63]
	v_mfma_f32_16x16x32_bf16 v[56:59], v[156:159], v[180:183], v[56:59]
	v_mfma_f32_16x16x32_bf16 v[44:47], v[148:151], v[200:203], v[44:47]
	v_mfma_f32_16x16x32_bf16 v[40:43], v[156:159], v[200:203], v[40:43]
	v_mfma_f32_16x16x32_bf16 v[28:31], v[148:151], v[208:211], v[28:31]
	v_mfma_f32_16x16x32_bf16 v[24:27], v[156:159], v[208:211], v[24:27]
	v_mfma_f32_16x16x32_bf16 v[12:15], v[148:151], v[216:219], v[12:15]
	v_mfma_f32_16x16x32_bf16 v[8:11], v[156:159], v[216:219], v[8:11]
	s_setprio 0
	s_setprio 1
	v_mfma_f32_16x16x32_bf16 v[52:55], v[160:163], v[176:179], v[52:55]
	v_mfma_f32_16x16x32_bf16 v[48:51], v[168:171], v[176:179], v[48:51]
	v_mfma_f32_16x16x32_bf16 v[36:39], v[160:163], v[184:187], v[36:39]
	v_mfma_f32_16x16x32_bf16 v[32:35], v[168:171], v[184:187], v[32:35]
	v_mfma_f32_16x16x32_bf16 v[20:23], v[160:163], v[204:207], v[20:23]
	v_mfma_f32_16x16x32_bf16 v[16:19], v[168:171], v[204:207], v[16:19]
	v_mfma_f32_16x16x32_bf16 v[4:7], v[160:163], v[212:215], v[4:7]
	v_mfma_f32_16x16x32_bf16 v[0:3], v[168:171], v[212:215], v[0:3]
	v_mfma_f32_16x16x32_bf16 v[52:55], v[164:167], v[180:183], v[52:55]
	v_mfma_f32_16x16x32_bf16 v[48:51], v[172:175], v[180:183], v[48:51]
	v_mfma_f32_16x16x32_bf16 v[36:39], v[164:167], v[200:203], v[36:39]
	v_mfma_f32_16x16x32_bf16 v[32:35], v[172:175], v[200:203], v[32:35]
	v_mfma_f32_16x16x32_bf16 v[20:23], v[164:167], v[208:211], v[20:23]
	v_mfma_f32_16x16x32_bf16 v[16:19], v[172:175], v[208:211], v[16:19]
	v_mfma_f32_16x16x32_bf16 v[4:7], v[164:167], v[216:219], v[4:7]
	v_mfma_f32_16x16x32_bf16 v[0:3], v[172:175], v[216:219], v[0:3]
	s_setprio 0
	s_barrier
; #define PG8_STAGE(bufoff, gbase, voff) do { _Pragma("unroll") for (int _i = 0; _i < 2; ++_i) \
;         __builtin_amdgcn_global_load_lds((const unsigned*)((const char*)(gbase) + (voff)[_i]), (PG8_LAS unsigned*)(lds + (bufoff) + ldsw + _i * 8192), 16, 0, 0); } while (0)
; #define PG8_LDA(dst, b, h) do { _Pragma("unroll") for (int m = 0; m < 4; ++m) _Pragma("unroll") for (int k = 0; k < 2; ++k) dst[m][k] = *(const PG8_LAS bf16x8*)(lds + PG8_SA(b, h) + aoff + m * 2048 + k * 1024); } while (0)
; #define PG8_LDB(dst, b, h) do { _Pragma("unroll") for (int n = 0; n < 2; ++n) _Pragma("unroll") for (int k = 0; k < 2; ++k) dst[n][k] = *(const PG8_LAS bf16x8*)(lds + PG8_SB(b, h) + boff + n * 2048 + k * 1024); } while (0)
; #define PG8_MMA(ai, bj, At, Bt) do { __builtin_amdgcn_s_setprio(1); _Pragma("unroll") for (int m = 0; m < 4; ++m) _Pragma("unroll") for (int n = 0; n < 2; ++n) _Pragma("unroll") for (int k = 0; k < 2; ++k) \
;         acc[ai][bj][m][n] = __builtin_amdgcn_mfma_f32_16x16x32_bf16(Bt[n][k], At[m][k], acc[ai][bj][m][n], 0, 0, 0); __builtin_amdgcn_s_setprio(0); } while (0)
; #define PG8_WAIT_V(n) asm volatile("s_waitcnt vmcnt(" #n ")" ::: "memory")
; #define PG8_WAIT_L(n) asm volatile("s_waitcnt lgkmcnt(" #n ")" ::: "memory")
; #define PG8_BAR __builtin_amdgcn_s_barrier()
; #define PG8_SCHED __builtin_amdgcn_sched_barrier(0)
; template <class Epi, class Sched, bool ALIGN_EPI = false, bool SP2 = false>
; __device__ __forceinline__ void gemm_phase(PG8_LAS unsigned char* lds, const Gemm g, const Sched& S, const Epi& E, int tid_in) {
;     ...
;             PG8_LDB(B0, 1, 0); PG8_LDB(B1, 1, 1); PG8_SCHED; PG8_LDA(At, 1, 0); PG8_STAGE(PG8_SA(0, 1), a2 + hstepA, voffA);
;             PG8_WAIT_V(8); PG8_WAIT_L(0); PG8_BAR; PG8_MMA(0, 0, At, B0); PG8_MMA(0, 1, At, B1); PG8_BAR; PG8_SCHED;
;             PG8_LDA(At, 1, 1); PG8_STAGE(PG8_SB(1, 0), b3, voffB); PG8_STAGE(PG8_SB(1, 1), b3 + hstep, voffB); PG8_STAGE(PG8_SA(1, 0), a3, voffA);
;             PG8_WAIT_V(8); PG8_WAIT_L(0); PG8_BAR; PG8_MMA(1, 0, At, B0); PG8_MMA(1, 1, At, B1); PG8_BAR; PG8_SCHED;
;     ...
;         if constexpr (ALIGN_EPI) { if (wr == 0) PG8_BAR; }
	s_add_i32 s57, 0, 0x18000
	v_add_u32_e32 v147, s57, v145
	s_add_i32 s58, 0, 0x1c000
	ds_read_b128 v[140:143], v147
	ds_read_b128 v[148:151], v147 offset:1024
	ds_read_b128 v[152:155], v147 offset:2048
	ds_read_b128 v[156:159], v147 offset:3072
	v_add_u32_e32 v147, s58, v145
	ds_read_b128 v[160:163], v147
	ds_read_b128 v[164:167], v147 offset:1024
	ds_read_b128 v[168:171], v147 offset:2048
	ds_read_b128 v[172:175], v147 offset:3072
	s_add_u32 s30, s30, 0x40000
	s_addc_u32 s31, s31, 0
	s_mov_b32 m0, s44
	ds_read_b128 v[176:179], v146 offset:32768
	ds_read_b128 v[180:183], v146 offset:33792
	ds_read_b128 v[184:187], v146 offset:34816
	ds_read_b128 v[200:203], v146 offset:35840
	ds_read_b128 v[204:207], v146 offset:36864
	ds_read_b128 v[208:211], v146 offset:37888
	ds_read_b128 v[212:215], v146 offset:38912
	global_load_lds_dwordx4 v134, s[30:31]
	s_mov_b32 m0, s45
	ds_read_b128 v[216:219], v146 offset:39936
	global_load_lds_dwordx4 v130, s[30:31]
	s_waitcnt vmcnt(8)
	s_waitcnt lgkmcnt(0)
	s_barrier
	s_setprio 1
	s_waitcnt lgkmcnt(0)
	v_mfma_f32_16x16x32_bf16 v[124:127], v[140:143], v[176:179], v[124:127]
	v_mfma_f32_16x16x32_bf16 v[120:123], v[152:155], v[176:179], v[120:123]
	v_mfma_f32_16x16x32_bf16 v[108:111], v[140:143], v[184:187], v[108:111]
	v_mfma_f32_16x16x32_bf16 v[104:107], v[152:155], v[184:187], v[104:107]
	v_mfma_f32_16x16x32_bf16 v[92:95], v[140:143], v[204:207], v[92:95]
	v_mfma_f32_16x16x32_bf16 v[88:91], v[152:155], v[204:207], v[88:91]
	v_mfma_f32_16x16x32_bf16 v[76:79], v[140:143], v[212:215], v[76:79]
	v_mfma_f32_16x16x32_bf16 v[72:75], v[152:155], v[212:215], v[72:75]
	v_mfma_f32_16x16x32_bf16 v[124:127], v[148:151], v[180:183], v[124:127]
	v_mfma_f32_16x16x32_bf16 v[120:123], v[156:159], v[180:183], v[120:123]
	v_mfma_f32_16x16x32_bf16 v[108:111], v[148:151], v[200:203], v[108:111]
	v_mfma_f32_16x16x32_bf16 v[104:107], v[156:159], v[200:203], v[104:107]
	v_mfma_f32_16x16x32_bf16 v[92:95], v[148:151], v[208:211], v[92:95]
	v_mfma_f32_16x16x32_bf16 v[88:91], v[156:159], v[208:211], v[88:91]
	v_mfma_f32_16x16x32_bf16 v[76:79], v[148:151], v[216:219], v[76:79]
	v_mfma_f32_16x16x32_bf16 v[72:75], v[156:159], v[216:219], v[72:75]
	s_setprio 0
	s_setprio 1
	v_mfma_f32_16x16x32_bf16 v[116:119], v[160:163], v[176:179], v[116:119]
	v_mfma_f32_16x16x32_bf16 v[112:115], v[168:171], v[176:179], v[112:115]
	v_mfma_f32_16x16x32_bf16 v[100:103], v[160:163], v[184:187], v[100:103]
	v_mfma_f32_16x16x32_bf16 v[96:99], v[168:171], v[184:187], v[96:99]
	v_mfma_f32_16x16x32_bf16 v[84:87], v[160:163], v[204:207], v[84:87]
	v_mfma_f32_16x16x32_bf16 v[80:83], v[168:171], v[204:207], v[80:83]
	v_mfma_f32_16x16x32_bf16 v[68:71], v[160:163], v[212:215], v[68:71]
	v_mfma_f32_16x16x32_bf16 v[64:67], v[168:171], v[212:215], v[64:67]
	v_mfma_f32_16x16x32_bf16 v[116:119], v[164:167], v[180:183], v[116:119]
	v_mfma_f32_16x16x32_bf16 v[112:115], v[172:175], v[180:183], v[112:115]
	v_mfma_f32_16x16x32_bf16 v[100:103], v[164:167], v[200:203], v[100:103]
	v_mfma_f32_16x16x32_bf16 v[96:99], v[172:175], v[200:203], v[96:99]
	v_mfma_f32_16x16x32_bf16 v[84:87], v[164:167], v[208:211], v[84:87]
	v_mfma_f32_16x16x32_bf16 v[80:83], v[172:175], v[208:211], v[80:83]
	v_mfma_f32_16x16x32_bf16 v[68:71], v[164:167], v[216:219], v[68:71]
	v_mfma_f32_16x16x32_bf16 v[64:67], v[172:175], v[216:219], v[64:67]
	s_setprio 0
	s_barrier
	s_add_i32 s30, s57, s41
	s_mov_b32 m0, s30
	ds_read_b128 v[176:179], v146 offset:49152
	ds_read_b128 v[180:183], v146 offset:50176
	ds_read_b128 v[184:187], v146 offset:51200
	ds_read_b128 v[200:203], v146 offset:52224
	s_add_u32 s28, s28, 0x80
	s_addc_u32 s29, s29, 0
	global_load_lds_dwordx4 v132, s[28:29]
	s_add_i32 m0, s30, 0x2000
	ds_read_b128 v[204:207], v146 offset:53248
	global_load_lds_dwordx4 v128, s[28:29]
	s_add_u32 s28, s28, 0x40000
	s_addc_u32 s29, s29, 0
	s_add_i32 s30, s58, s41
	s_mov_b32 m0, s30
	ds_read_b128 v[208:211], v146 offset:54272
	global_load_lds_dwordx4 v132, s[28:29]
	s_add_i32 m0, s30, 0x2000
	ds_read_b128 v[212:215], v146 offset:55296
	global_load_lds_dwordx4 v128, s[28:29]
	s_mov_b32 m0, s46
	s_nop 0
	s_add_u32 s100, s100, 0x80
	s_addc_u32 s101, s101, 0
	global_load_lds_dwordx4 v134, s[100:101]
	s_mov_b32 m0, s47
	ds_read_b128 v[216:219], v146 offset:56320
	global_load_lds_dwordx4 v130, s[100:101]
	s_waitcnt vmcnt(8)
	s_waitcnt lgkmcnt(0)
	s_barrier
	s_setprio 1
	s_waitcnt lgkmcnt(0)
	v_mfma_f32_16x16x32_bf16 v[60:63], v[140:143], v[176:179], v[60:63]
	v_mfma_f32_16x16x32_bf16 v[56:59], v[152:155], v[176:179], v[56:59]
	v_mfma_f32_16x16x32_bf16 v[44:47], v[140:143], v[184:187], v[44:47]
	v_mfma_f32_16x16x32_bf16 v[40:43], v[152:155], v[184:187], v[40:43]
	v_mfma_f32_16x16x32_bf16 v[28:31], v[140:143], v[204:207], v[28:31]
	v_mfma_f32_16x16x32_bf16 v[24:27], v[152:155], v[204:207], v[24:27]
	v_mfma_f32_16x16x32_bf16 v[12:15], v[140:143], v[212:215], v[12:15]
	v_mfma_f32_16x16x32_bf16 v[8:11], v[152:155], v[212:215], v[8:11]
	v_mfma_f32_16x16x32_bf16 v[60:63], v[148:151], v[180:183], v[60:63]
	v_mfma_f32_16x16x32_bf16 v[56:59], v[156:159], v[180:183], v[56:59]
	v_mfma_f32_16x16x32_bf16 v[44:47], v[148:151], v[200:203], v[44:47]
	v_mfma_f32_16x16x32_bf16 v[40:43], v[156:159], v[200:203], v[40:43]
	v_mfma_f32_16x16x32_bf16 v[28:31], v[148:151], v[208:211], v[28:31]
	v_mfma_f32_16x16x32_bf16 v[24:27], v[156:159], v[208:211], v[24:27]
	v_mfma_f32_16x16x32_bf16 v[12:15], v[148:151], v[216:219], v[12:15]
	v_mfma_f32_16x16x32_bf16 v[8:11], v[156:159], v[216:219], v[8:11]
	s_setprio 0
	s_setprio 1
	v_mfma_f32_16x16x32_bf16 v[52:55], v[160:163], v[176:179], v[52:55]
	v_mfma_f32_16x16x32_bf16 v[48:51], v[168:171], v[176:179], v[48:51]
	v_mfma_f32_16x16x32_bf16 v[36:39], v[160:163], v[184:187], v[36:39]
	v_mfma_f32_16x16x32_bf16 v[32:35], v[168:171], v[184:187], v[32:35]
	v_mfma_f32_16x16x32_bf16 v[20:23], v[160:163], v[204:207], v[20:23]
	v_mfma_f32_16x16x32_bf16 v[16:19], v[168:171], v[204:207], v[16:19]
	v_mfma_f32_16x16x32_bf16 v[4:7], v[160:163], v[212:215], v[4:7]
	v_mfma_f32_16x16x32_bf16 v[0:3], v[168:171], v[212:215], v[0:3]
	v_mfma_f32_16x16x32_bf16 v[52:55], v[164:167], v[180:183], v[52:55]
	v_mfma_f32_16x16x32_bf16 v[48:51], v[172:175], v[180:183], v[48:51]
	v_mfma_f32_16x16x32_bf16 v[36:39], v[164:167], v[200:203], v[36:39]
	v_mfma_f32_16x16x32_bf16 v[32:35], v[172:175], v[200:203], v[32:35]
	v_mfma_f32_16x16x32_bf16 v[20:23], v[164:167], v[208:211], v[20:23]
	v_mfma_f32_16x16x32_bf16 v[16:19], v[172:175], v[208:211], v[16:19]
	v_mfma_f32_16x16x32_bf16 v[4:7], v[164:167], v[216:219], v[4:7]
	v_mfma_f32_16x16x32_bf16 v[0:3], v[172:175], v[216:219], v[0:3]
	s_setprio 0
	s_barrier
	s_add_i32 s56, s56, 2
	s_add_u32 s54, s54, 0x100
	s_addc_u32 s55, s55, 0
	s_add_u32 s26, s26, 0x100
	s_addc_u32 s27, s27, 0
	s_cmp_gt_u32 s56, 13
	s_cbranch_scc0 .LBB0_691
	v_readlane_b32 s56, v255, 17
	s_and_b64 vcc, exec, s[10:11]
	s_mov_b64 s[30:31], 0x10000600
	v_readlane_b32 s57, v255, 18
	v_readlane_b32 s58, v255, 19
	v_readlane_b32 s59, v255, 20
	s_cbranch_vccz .LBB0_694
	s_barrier

; #define PG8_STAGE(bufoff, gbase, voff) do { _Pragma("unroll") for (int _i = 0; _i < 2; ++_i) \
;         __builtin_amdgcn_global_load_lds((const unsigned*)((const char*)(gbase) + (voff)[_i]), (PG8_LAS unsigned*)(lds + (bufoff) + ldsw + _i * 8192), 16, 0, 0); } while (0)
; #define PG8_LDA(dst, b, h) do { _Pragma("unroll") for (int m = 0; m < 4; ++m) _Pragma("unroll") for (int k = 0; k < 2; ++k) dst[m][k] = *(const PG8_LAS bf16x8*)(lds + PG8_SA(b, h) + aoff + m * 2048 + k * 1024); } while (0)
; #define PG8_LDB(dst, b, h) do { _Pragma("unroll") for (int n = 0; n < 2; ++n) _Pragma("unroll") for (int k = 0; k < 2; ++k) dst[n][k] = *(const PG8_LAS bf16x8*)(lds + PG8_SB(b, h) + boff + n * 2048 + k * 1024); } while (0)
; #define PG8_MMA(ai, bj, At, Bt) do { __builtin_amdgcn_s_setprio(1); _Pragma("unroll") for (int m = 0; m < 4; ++m) _Pragma("unroll") for (int n = 0; n < 2; ++n) _Pragma("unroll") for (int k = 0; k < 2; ++k) \
;         acc[ai][bj][m][n] = __builtin_amdgcn_mfma_f32_16x16x32_bf16(Bt[n][k], At[m][k], acc[ai][bj][m][n], 0, 0, 0); __builtin_amdgcn_s_setprio(0); } while (0)
; #define PG8_WAIT_V(n) asm volatile("s_waitcnt vmcnt(" #n ")" ::: "memory")
; #define PG8_WAIT_L(n) asm volatile("s_waitcnt lgkmcnt(" #n ")" ::: "memory")
; #define PG8_BAR __builtin_amdgcn_s_barrier()
; #define PG8_SCHED __builtin_amdgcn_sched_barrier(0)
; template <class Epi, class Sched, bool ALIGN_EPI = false, bool SP2 = false>
; __device__ __forceinline__ void gemm_phase(PG8_LAS unsigned char* lds, const Gemm g, const Sched& S, const Epi& E, int tid_in) {
;     ...
;             const bool last = (t == nt - 2);
;             const char* a1 = cA + (size_t)(t + 1) * kstep;
;             const char* a2 = last ? nA : cA + (size_t)(t + 2) * kstep; const char* b2 = last ? nB : cB + (size_t)(t + 2) * kstep;
;             const char* a3 = a2 + kstep; const char* b3 = b2 + kstep;
;             if (last && has_next) S.a_ready(nxt);
;             if constexpr (SP2) {
;             PG8_LDB(B0, 0, 0); PG8_LDB(B1, 0, 1); PG8_SCHED; PG8_LDA(At, 0, 0); PG8_STAGE(PG8_SA(1, 1), a1 + hstepA, voffA);
;             PG8_WAIT_V(8); PG8_WAIT_L(0); PG8_BAR; PG8_MMA(0, 0, At, B0); PG8_MMA(0, 1, At, B1); PG8_BAR; PG8_SCHED;
;             PG8_LDA(At, 0, 1); PG8_STAGE(PG8_SB(0, 0), b2, voffB); PG8_STAGE(PG8_SB(0, 1), b2 + hstep, voffB); PG8_STAGE(PG8_SA(0, 0), a2, voffA);
.LBB0_782:
	s_add_u32 s26, s24, 0xfffc0080
	s_addc_u32 s27, s25, -1
	s_add_i32 s54, 0, 0x10000
	s_cmp_eq_u32 s53, 28
	s_cselect_b32 s29, s15, s27
	s_cselect_b32 s28, s49, s26
	s_cselect_b32 s27, s13, s52
	s_cselect_b32 s26, s50, s51
	s_add_i32 s56, 0, 0x14000
	v_add_u32_e32 v158, s54, v156
	v_add_u32_e32 v174, s56, v156
	ds_read_b128 v[96:99], v158
	ds_read_b128 v[100:103], v158 offset:1024
	ds_read_b128 v[150:153], v158 offset:2048
	ds_read_b128 v[158:161], v158 offset:3072
	ds_read_b128 v[162:165], v174
	ds_read_b128 v[166:169], v174 offset:1024
	ds_read_b128 v[170:173], v174 offset:2048
	ds_read_b128 v[174:177], v174 offset:3072
	s_add_i32 m0, s38, 0xc000
	ds_read_b128 v[178:181], v157
	ds_read_b128 v[182:185], v157 offset:1024
	ds_read_b128 v[186:189], v157 offset:2048
	ds_read_b128 v[200:203], v157 offset:3072
	ds_read_b128 v[204:207], v157 offset:4096
	ds_read_b128 v[208:211], v157 offset:5120
	ds_read_b128 v[212:215], v157 offset:6144
	global_load_lds_dwordx4 v148, s[24:25]
	s_add_i32 m0, s38, 0xe000
	ds_read_b128 v[216:219], v157 offset:7168
	global_load_lds_dwordx4 v146, s[24:25]
	s_waitcnt vmcnt(8)
	s_waitcnt lgkmcnt(0)
	s_barrier
	s_setprio 1
	s_waitcnt lgkmcnt(0)
	v_mfma_f32_16x16x32_bf16 v[132:135], v[96:99], v[178:181], v[132:135]
	v_mfma_f32_16x16x32_bf16 v[128:131], v[150:153], v[178:181], v[128:131]
	v_mfma_f32_16x16x32_bf16 v[124:127], v[96:99], v[186:189], v[124:127]
	v_mfma_f32_16x16x32_bf16 v[120:123], v[150:153], v[186:189], v[120:123]
	v_mfma_f32_16x16x32_bf16 v[116:119], v[96:99], v[204:207], v[116:119]
	v_mfma_f32_16x16x32_bf16 v[112:115], v[150:153], v[204:207], v[112:115]
	v_mfma_f32_16x16x32_bf16 v[108:111], v[96:99], v[212:215], v[108:111]
	v_mfma_f32_16x16x32_bf16 v[104:107], v[150:153], v[212:215], v[104:107]
	v_mfma_f32_16x16x32_bf16 v[132:135], v[100:103], v[182:185], v[132:135]
	v_mfma_f32_16x16x32_bf16 v[128:131], v[158:161], v[182:185], v[128:131]
	v_mfma_f32_16x16x32_bf16 v[124:127], v[100:103], v[200:203], v[124:127]
	v_mfma_f32_16x16x32_bf16 v[120:123], v[158:161], v[200:203], v[120:123]
	v_mfma_f32_16x16x32_bf16 v[116:119], v[100:103], v[208:211], v[116:119]
	v_mfma_f32_16x16x32_bf16 v[112:115], v[158:161], v[208:211], v[112:115]
	v_mfma_f32_16x16x32_bf16 v[108:111], v[100:103], v[216:219], v[108:111]
	v_mfma_f32_16x16x32_bf16 v[104:107], v[158:161], v[216:219], v[104:107]
	s_setprio 0
	s_setprio 1
	v_mfma_f32_16x16x32_bf16 v[60:63], v[162:165], v[178:181], v[60:63]
	v_mfma_f32_16x16x32_bf16 v[56:59], v[170:173], v[178:181], v[56:59]
	v_mfma_f32_16x16x32_bf16 v[52:55], v[162:165], v[186:189], v[52:55]
	v_mfma_f32_16x16x32_bf16 v[48:51], v[170:173], v[186:189], v[48:51]
	v_mfma_f32_16x16x32_bf16 v[44:47], v[162:165], v[204:207], v[44:47]
	v_mfma_f32_16x16x32_bf16 v[40:43], v[170:173], v[204:207], v[40:43]
	v_mfma_f32_16x16x32_bf16 v[36:39], v[162:165], v[212:215], v[36:39]
	v_mfma_f32_16x16x32_bf16 v[32:35], v[170:173], v[212:215], v[32:35]
	v_mfma_f32_16x16x32_bf16 v[60:63], v[166:169], v[182:185], v[60:63]
	v_mfma_f32_16x16x32_bf16 v[56:59], v[174:177], v[182:185], v[56:59]
	v_mfma_f32_16x16x32_bf16 v[52:55], v[166:169], v[200:203], v[52:55]
	v_mfma_f32_16x16x32_bf16 v[48:51], v[174:177], v[200:203], v[48:51]
	v_mfma_f32_16x16x32_bf16 v[44:47], v[166:169], v[208:211], v[44:47]
	v_mfma_f32_16x16x32_bf16 v[40:43], v[174:177], v[208:211], v[40:43]
	v_mfma_f32_16x16x32_bf16 v[36:39], v[166:169], v[216:219], v[36:39]
	v_mfma_f32_16x16x32_bf16 v[32:35], v[174:177], v[216:219], v[32:35]
	s_setprio 0
	s_barrier
	s_add_i32 s54, s54, s35
	s_mov_b64 s[100:101], s[26:27]
	s_mov_b32 m0, s54
	ds_read_b128 v[178:181], v157 offset:16384
	ds_read_b128 v[182:185], v157 offset:17408
	ds_read_b128 v[186:189], v157 offset:18432
	ds_read_b128 v[200:203], v157 offset:19456
	ds_read_b128 v[204:207], v157 offset:20480
	global_load_lds_dwordx4 v190, s[100:101]
	s_add_i32 m0, s54, 0x2000
	s_add_u32 s54, s26, 0x80000
	s_addc_u32 s55, s27, 0
	s_add_i32 s56, s56, s35
	global_load_lds_dwordx4 v136, s[100:101]
	s_mov_b32 m0, s56
	v_lshl_add_u64 v[232:233], s[28:29], 0, v[138:139]
	global_load_lds_dwordx4 v190, s[54:55]
	s_add_i32 m0, s56, 0x2000
	ds_read_b128 v[208:211], v157 offset:21504
	global_load_lds_dwordx4 v136, s[54:55]
	v_lshl_add_u64 v[230:231], s[28:29], 0, v[140:141]
	s_mov_b32 m0, s38
	ds_read_b128 v[212:215], v157 offset:22528
	global_load_lds_dwordx4 v[230:231], off
	s_mov_b32 m0, s40
	ds_read_b128 v[216:219], v157 offset:23552
	global_load_lds_dwordx4 v[232:233], off
	s_waitcnt vmcnt(8)
	s_waitcnt lgkmcnt(0)
	s_barrier
; #define PG8_STAGE(bufoff, gbase, voff) do { _Pragma("unroll") for (int _i = 0; _i < 2; ++_i) \
;         __builtin_amdgcn_global_load_lds((const unsigned*)((const char*)(gbase) + (voff)[_i]), (PG8_LAS unsigned*)(lds + (bufoff) + ldsw + _i * 8192), 16, 0, 0); } while (0)
; #define PG8_LDA(dst, b, h) do { _Pragma("unroll") for (int m = 0; m < 4; ++m) _Pragma("unroll") for (int k = 0; k < 2; ++k) dst[m][k] = *(const PG8_LAS bf16x8*)(lds + PG8_SA(b, h) + aoff + m * 2048 + k * 1024); } while (0)
; #define PG8_LDB(dst, b, h) do { _Pragma("unroll") for (int n = 0; n < 2; ++n) _Pragma("unroll") for (int k = 0; k < 2; ++k) dst[n][k] = *(const PG8_LAS bf16x8*)(lds + PG8_SB(b, h) + boff + n * 2048 + k * 1024); } while (0)
; #define PG8_MMA(ai, bj, At, Bt) do { __builtin_amdgcn_s_setprio(1); _Pragma("unroll") for (int m = 0; m < 4; ++m) _Pragma("unroll") for (int n = 0; n < 2; ++n) _Pragma("unroll") for (int k = 0; k < 2; ++k) \
;         acc[ai][bj][m][n] = __builtin_amdgcn_mfma_f32_16x16x32_bf16(Bt[n][k], At[m][k], acc[ai][bj][m][n], 0, 0, 0); __builtin_amdgcn_s_setprio(0); } while (0)
; #define PG8_WAIT_V(n) asm volatile("s_waitcnt vmcnt(" #n ")" ::: "memory")
; #define PG8_WAIT_L(n) asm volatile("s_waitcnt lgkmcnt(" #n ")" ::: "memory")
; #define PG8_BAR __builtin_amdgcn_s_barrier()
; #define PG8_SCHED __builtin_amdgcn_sched_barrier(0)
; template <class Epi, class Sched, bool ALIGN_EPI = false, bool SP2 = false>
; __device__ __forceinline__ void gemm_phase(PG8_LAS unsigned char* lds, const Gemm g, const Sched& S, const Epi& E, int tid_in) {
;     ...
;             PG8_WAIT_V(8); PG8_WAIT_L(0); PG8_BAR; PG8_MMA(1, 0, At, B0); PG8_MMA(1, 1, At, B1); PG8_BAR; PG8_SCHED;
;             PG8_LDB(B0, 1, 0); PG8_LDB(B1, 1, 1); PG8_SCHED; PG8_LDA(At, 1, 0); PG8_STAGE(PG8_SA(0, 1), a2 + hstepA, voffA);
;             PG8_WAIT_V(8); PG8_WAIT_L(0); PG8_BAR; PG8_MMA(0, 0, At, B0); PG8_MMA(0, 1, At, B1); PG8_BAR; PG8_SCHED;
	s_setprio 1
	s_waitcnt lgkmcnt(0)
	v_mfma_f32_16x16x32_bf16 v[92:95], v[96:99], v[178:181], v[92:95]
	v_mfma_f32_16x16x32_bf16 v[88:91], v[150:153], v[178:181], v[88:91]
	v_mfma_f32_16x16x32_bf16 v[84:87], v[96:99], v[186:189], v[84:87]
	v_mfma_f32_16x16x32_bf16 v[80:83], v[150:153], v[186:189], v[80:83]
	v_mfma_f32_16x16x32_bf16 v[76:79], v[96:99], v[204:207], v[76:79]
	v_mfma_f32_16x16x32_bf16 v[72:75], v[150:153], v[204:207], v[72:75]
	v_mfma_f32_16x16x32_bf16 v[68:71], v[96:99], v[212:215], v[68:71]
	v_mfma_f32_16x16x32_bf16 v[64:67], v[150:153], v[212:215], v[64:67]
	v_mfma_f32_16x16x32_bf16 v[92:95], v[100:103], v[182:185], v[92:95]
	v_mfma_f32_16x16x32_bf16 v[88:91], v[158:161], v[182:185], v[88:91]
	v_mfma_f32_16x16x32_bf16 v[84:87], v[100:103], v[200:203], v[84:87]
	v_mfma_f32_16x16x32_bf16 v[80:83], v[158:161], v[200:203], v[80:83]
	v_mfma_f32_16x16x32_bf16 v[76:79], v[100:103], v[208:211], v[76:79]
	v_mfma_f32_16x16x32_bf16 v[72:75], v[158:161], v[208:211], v[72:75]
	v_mfma_f32_16x16x32_bf16 v[68:71], v[100:103], v[216:219], v[68:71]
	v_mfma_f32_16x16x32_bf16 v[64:67], v[158:161], v[216:219], v[64:67]
	s_setprio 0
	s_setprio 1
	v_mfma_f32_16x16x32_bf16 v[28:31], v[162:165], v[178:181], v[28:31]
	v_mfma_f32_16x16x32_bf16 v[24:27], v[170:173], v[178:181], v[24:27]
	v_mfma_f32_16x16x32_bf16 v[20:23], v[162:165], v[186:189], v[20:23]
	v_mfma_f32_16x16x32_bf16 v[16:19], v[170:173], v[186:189], v[16:19]
	v_mfma_f32_16x16x32_bf16 v[12:15], v[162:165], v[204:207], v[12:15]
	v_mfma_f32_16x16x32_bf16 v[8:11], v[170:173], v[204:207], v[8:11]
	v_mfma_f32_16x16x32_bf16 v[4:7], v[162:165], v[212:215], v[4:7]
	v_mfma_f32_16x16x32_bf16 v[0:3], v[170:173], v[212:215], v[0:3]
	v_mfma_f32_16x16x32_bf16 v[28:31], v[166:169], v[182:185], v[28:31]
	v_mfma_f32_16x16x32_bf16 v[24:27], v[174:177], v[182:185], v[24:27]
	v_mfma_f32_16x16x32_bf16 v[20:23], v[166:169], v[200:203], v[20:23]
	v_mfma_f32_16x16x32_bf16 v[16:19], v[174:177], v[200:203], v[16:19]
	v_mfma_f32_16x16x32_bf16 v[12:15], v[166:169], v[208:211], v[12:15]
	v_mfma_f32_16x16x32_bf16 v[8:11], v[174:177], v[208:211], v[8:11]
	v_mfma_f32_16x16x32_bf16 v[4:7], v[166:169], v[216:219], v[4:7]
	v_mfma_f32_16x16x32_bf16 v[0:3], v[174:177], v[216:219], v[0:3]
	s_setprio 0
	s_barrier
	s_add_i32 s54, 0, 0x18000
	s_add_i32 s55, 0, 0x1c000
	v_add_u32_e32 v158, s54, v156
	v_add_u32_e32 v174, s55, v156
	ds_read_b128 v[96:99], v158
	ds_read_b128 v[100:103], v158 offset:1024
	ds_read_b128 v[150:153], v158 offset:2048
	ds_read_b128 v[158:161], v158 offset:3072
	ds_read_b128 v[162:165], v174
	ds_read_b128 v[166:169], v174 offset:1024
	ds_read_b128 v[170:173], v174 offset:2048
	ds_read_b128 v[174:177], v174 offset:3072
	s_add_u32 s28, s28, 0x40000
	s_addc_u32 s29, s29, 0
	s_mov_b32 m0, s41
	ds_read_b128 v[178:181], v157 offset:32768
	ds_read_b128 v[182:185], v157 offset:33792
	ds_read_b128 v[186:189], v157 offset:34816
	ds_read_b128 v[200:203], v157 offset:35840
	ds_read_b128 v[204:207], v157 offset:36864
	ds_read_b128 v[208:211], v157 offset:37888
	ds_read_b128 v[212:215], v157 offset:38912
	global_load_lds_dwordx4 v140, s[28:29]
	s_mov_b32 m0, s42
	ds_read_b128 v[216:219], v157 offset:39936
	global_load_lds_dwordx4 v138, s[28:29]
	s_waitcnt vmcnt(8)
	s_waitcnt lgkmcnt(0)
	s_barrier
	s_setprio 1
	s_waitcnt lgkmcnt(0)
	v_mfma_f32_16x16x32_bf16 v[132:135], v[96:99], v[178:181], v[132:135]
	v_mfma_f32_16x16x32_bf16 v[128:131], v[150:153], v[178:181], v[128:131]
	v_mfma_f32_16x16x32_bf16 v[124:127], v[96:99], v[186:189], v[124:127]
	v_mfma_f32_16x16x32_bf16 v[120:123], v[150:153], v[186:189], v[120:123]
	v_mfma_f32_16x16x32_bf16 v[116:119], v[96:99], v[204:207], v[116:119]
	v_mfma_f32_16x16x32_bf16 v[112:115], v[150:153], v[204:207], v[112:115]
	v_mfma_f32_16x16x32_bf16 v[108:111], v[96:99], v[212:215], v[108:111]
	v_mfma_f32_16x16x32_bf16 v[104:107], v[150:153], v[212:215], v[104:107]
	v_mfma_f32_16x16x32_bf16 v[132:135], v[100:103], v[182:185], v[132:135]
	v_mfma_f32_16x16x32_bf16 v[128:131], v[158:161], v[182:185], v[128:131]
	v_mfma_f32_16x16x32_bf16 v[124:127], v[100:103], v[200:203], v[124:127]
	v_mfma_f32_16x16x32_bf16 v[120:123], v[158:161], v[200:203], v[120:123]
	v_mfma_f32_16x16x32_bf16 v[116:119], v[100:103], v[208:211], v[116:119]
	v_mfma_f32_16x16x32_bf16 v[112:115], v[158:161], v[208:211], v[112:115]
	v_mfma_f32_16x16x32_bf16 v[108:111], v[100:103], v[216:219], v[108:111]
	v_mfma_f32_16x16x32_bf16 v[104:107], v[158:161], v[216:219], v[104:107]
	s_setprio 0
	s_setprio 1
	v_mfma_f32_16x16x32_bf16 v[60:63], v[162:165], v[178:181], v[60:63]
	v_mfma_f32_16x16x32_bf16 v[56:59], v[170:173], v[178:181], v[56:59]
	v_mfma_f32_16x16x32_bf16 v[52:55], v[162:165], v[186:189], v[52:55]
	v_mfma_f32_16x16x32_bf16 v[48:51], v[170:173], v[186:189], v[48:51]
	v_mfma_f32_16x16x32_bf16 v[44:47], v[162:165], v[204:207], v[44:47]
	v_mfma_f32_16x16x32_bf16 v[40:43], v[170:173], v[204:207], v[40:43]
	v_mfma_f32_16x16x32_bf16 v[36:39], v[162:165], v[212:215], v[36:39]
	v_mfma_f32_16x16x32_bf16 v[32:35], v[170:173], v[212:215], v[32:35]
	v_mfma_f32_16x16x32_bf16 v[60:63], v[166:169], v[182:185], v[60:63]
	v_mfma_f32_16x16x32_bf16 v[56:59], v[174:177], v[182:185], v[56:59]
	v_mfma_f32_16x16x32_bf16 v[52:55], v[166:169], v[200:203], v[52:55]
	v_mfma_f32_16x16x32_bf16 v[48:51], v[174:177], v[200:203], v[48:51]
	v_mfma_f32_16x16x32_bf16 v[44:47], v[166:169], v[208:211], v[44:47]
	v_mfma_f32_16x16x32_bf16 v[40:43], v[174:177], v[208:211], v[40:43]
	v_mfma_f32_16x16x32_bf16 v[36:39], v[166:169], v[216:219], v[36:39]
	v_mfma_f32_16x16x32_bf16 v[32:35], v[174:177], v[216:219], v[32:35]
	s_setprio 0
	s_barrier
; #define PG8_STAGE(bufoff, gbase, voff) do { _Pragma("unroll") for (int _i = 0; _i < 2; ++_i) \
;         __builtin_amdgcn_global_load_lds((const unsigned*)((const char*)(gbase) + (voff)[_i]), (PG8_LAS unsigned*)(lds + (bufoff) + ldsw + _i * 8192), 16, 0, 0); } while (0)
; #define PG8_LDA(dst, b, h) do { _Pragma("unroll") for (int m = 0; m < 4; ++m) _Pragma("unroll") for (int k = 0; k < 2; ++k) dst[m][k] = *(const PG8_LAS bf16x8*)(lds + PG8_SA(b, h) + aoff + m * 2048 + k * 1024); } while (0)
; #define PG8_MMA(ai, bj, At, Bt) do { __builtin_amdgcn_s_setprio(1); _Pragma("unroll") for (int m = 0; m < 4; ++m) _Pragma("unroll") for (int n = 0; n < 2; ++n) _Pragma("unroll") for (int k = 0; k < 2; ++k) \
;         acc[ai][bj][m][n] = __builtin_amdgcn_mfma_f32_16x16x32_bf16(Bt[n][k], At[m][k], acc[ai][bj][m][n], 0, 0, 0); __builtin_amdgcn_s_setprio(0); } while (0)
; #define PG8_WAIT_V(n) asm volatile("s_waitcnt vmcnt(" #n ")" ::: "memory")
; #define PG8_WAIT_L(n) asm volatile("s_waitcnt lgkmcnt(" #n ")" ::: "memory")
; #define PG8_BAR __builtin_amdgcn_s_barrier()
; #define PG8_SCHED __builtin_amdgcn_sched_barrier(0)
; template <class Epi, class Sched, bool ALIGN_EPI = false, bool SP2 = false>
; __device__ __forceinline__ void gemm_phase(PG8_LAS unsigned char* lds, const Gemm g, const Sched& S, const Epi& E, int tid_in) {
;     ...
;             PG8_LDA(At, 1, 1); PG8_STAGE(PG8_SB(1, 0), b3, voffB); PG8_STAGE(PG8_SB(1, 1), b3 + hstep, voffB); PG8_STAGE(PG8_SA(1, 0), a3, voffA);
;             PG8_WAIT_V(8); PG8_WAIT_L(0); PG8_BAR; PG8_MMA(1, 0, At, B0); PG8_MMA(1, 1, At, B1); PG8_BAR; PG8_SCHED;
;     ...
;         if constexpr (ALIGN_EPI) { if (wr == 0) PG8_BAR; }
	s_add_i32 s28, s54, s35
	s_mov_b32 m0, s28
	ds_read_b128 v[178:181], v157 offset:49152
	ds_read_b128 v[182:185], v157 offset:50176
	ds_read_b128 v[186:189], v157 offset:51200
	ds_read_b128 v[200:203], v157 offset:52224
	s_add_u32 s100, s100, 0x80
	s_addc_u32 s101, s101, 0
	global_load_lds_dwordx4 v190, s[100:101]
	s_add_i32 m0, s28, 0x2000
	s_add_u32 s26, s26, 0x80080
	s_addc_u32 s27, s27, 0
	s_add_i32 s28, s55, s35
	global_load_lds_dwordx4 v136, s[100:101]
	s_mov_b32 m0, s28
	ds_read_b128 v[204:207], v157 offset:53248
	global_load_lds_dwordx4 v190, s[26:27]
	s_add_i32 m0, s28, 0x2000
	ds_read_b128 v[208:211], v157 offset:54272
	global_load_lds_dwordx4 v136, s[26:27]
	v_lshl_add_u64 v[226:227], v[230:231], 0, s[0:1]
	s_mov_b32 m0, s45
	ds_read_b128 v[212:215], v157 offset:55296
	global_load_lds_dwordx4 v[226:227], off
	v_lshl_add_u64 v[226:227], v[232:233], 0, s[0:1]
	s_mov_b32 m0, s46
	ds_read_b128 v[216:219], v157 offset:56320
	global_load_lds_dwordx4 v[226:227], off
	s_waitcnt vmcnt(8)
	s_waitcnt lgkmcnt(0)
	s_barrier
	s_setprio 1
	s_waitcnt lgkmcnt(0)
	v_mfma_f32_16x16x32_bf16 v[92:95], v[96:99], v[178:181], v[92:95]
	v_mfma_f32_16x16x32_bf16 v[88:91], v[150:153], v[178:181], v[88:91]
	v_mfma_f32_16x16x32_bf16 v[84:87], v[96:99], v[186:189], v[84:87]
	v_mfma_f32_16x16x32_bf16 v[80:83], v[150:153], v[186:189], v[80:83]
	v_mfma_f32_16x16x32_bf16 v[76:79], v[96:99], v[204:207], v[76:79]
	v_mfma_f32_16x16x32_bf16 v[72:75], v[150:153], v[204:207], v[72:75]
	v_mfma_f32_16x16x32_bf16 v[68:71], v[96:99], v[212:215], v[68:71]
	v_mfma_f32_16x16x32_bf16 v[64:67], v[150:153], v[212:215], v[64:67]
	v_mfma_f32_16x16x32_bf16 v[92:95], v[100:103], v[182:185], v[92:95]
	v_mfma_f32_16x16x32_bf16 v[88:91], v[158:161], v[182:185], v[88:91]
	v_mfma_f32_16x16x32_bf16 v[84:87], v[100:103], v[200:203], v[84:87]
	v_mfma_f32_16x16x32_bf16 v[80:83], v[158:161], v[200:203], v[80:83]
	v_mfma_f32_16x16x32_bf16 v[76:79], v[100:103], v[208:211], v[76:79]
	v_mfma_f32_16x16x32_bf16 v[72:75], v[158:161], v[208:211], v[72:75]
	v_mfma_f32_16x16x32_bf16 v[68:71], v[100:103], v[216:219], v[68:71]
	v_mfma_f32_16x16x32_bf16 v[64:67], v[158:161], v[216:219], v[64:67]
	s_setprio 0
	s_setprio 1
	v_mfma_f32_16x16x32_bf16 v[28:31], v[162:165], v[178:181], v[28:31]
	v_mfma_f32_16x16x32_bf16 v[24:27], v[170:173], v[178:181], v[24:27]
	v_mfma_f32_16x16x32_bf16 v[20:23], v[162:165], v[186:189], v[20:23]
	v_mfma_f32_16x16x32_bf16 v[16:19], v[170:173], v[186:189], v[16:19]
	v_mfma_f32_16x16x32_bf16 v[12:15], v[162:165], v[204:207], v[12:15]
	v_mfma_f32_16x16x32_bf16 v[8:11], v[170:173], v[204:207], v[8:11]
	v_mfma_f32_16x16x32_bf16 v[4:7], v[162:165], v[212:215], v[4:7]
	v_mfma_f32_16x16x32_bf16 v[0:3], v[170:173], v[212:215], v[0:3]
	v_mfma_f32_16x16x32_bf16 v[28:31], v[166:169], v[182:185], v[28:31]
	v_mfma_f32_16x16x32_bf16 v[24:27], v[174:177], v[182:185], v[24:27]
	v_mfma_f32_16x16x32_bf16 v[20:23], v[166:169], v[200:203], v[20:23]
	v_mfma_f32_16x16x32_bf16 v[16:19], v[174:177], v[200:203], v[16:19]
	v_mfma_f32_16x16x32_bf16 v[12:15], v[166:169], v[208:211], v[12:15]
	v_mfma_f32_16x16x32_bf16 v[8:11], v[174:177], v[208:211], v[8:11]
	v_mfma_f32_16x16x32_bf16 v[4:7], v[166:169], v[216:219], v[4:7]
	v_mfma_f32_16x16x32_bf16 v[0:3], v[174:177], v[216:219], v[0:3]
	s_setprio 0
	s_barrier
	s_add_i32 s53, s53, 2
	s_add_u32 s51, s51, 0x100
	s_addc_u32 s52, s52, 0
	s_add_u32 s24, s24, 0x100
	s_addc_u32 s25, s25, 0
	s_cmp_gt_u32 s53, 29
	s_cbranch_scc0 .LBB0_782
	s_and_b64 vcc, exec, s[8:9]
	s_cbranch_vccz .LBB0_785
	s_barrier

; #define PG8_STAGE(bufoff, gbase, voff) do { _Pragma("unroll") for (int _i = 0; _i < 2; ++_i) \
;         __builtin_amdgcn_global_load_lds((const unsigned*)((const char*)(gbase) + (voff)[_i]), (PG8_LAS unsigned*)(lds + (bufoff) + ldsw + _i * 8192), 16, 0, 0); } while (0)
; #define PG8_LDA(dst, b, h) do { _Pragma("unroll") for (int m = 0; m < 4; ++m) _Pragma("unroll") for (int k = 0; k < 2; ++k) dst[m][k] = *(const PG8_LAS bf16x8*)(lds + PG8_SA(b, h) + aoff + m * 2048 + k * 1024); } while (0)
; #define PG8_LDB(dst, b, h) do { _Pragma("unroll") for (int n = 0; n < 2; ++n) _Pragma("unroll") for (int k = 0; k < 2; ++k) dst[n][k] = *(const PG8_LAS bf16x8*)(lds + PG8_SB(b, h) + boff + n * 2048 + k * 1024); } while (0)
; #define PG8_MMA(ai, bj, At, Bt) do { __builtin_amdgcn_s_setprio(1); _Pragma("unroll") for (int m = 0; m < 4; ++m) _Pragma("unroll") for (int n = 0; n < 2; ++n) _Pragma("unroll") for (int k = 0; k < 2; ++k) \
;         acc[ai][bj][m][n] = __builtin_amdgcn_mfma_f32_16x16x32_bf16(Bt[n][k], At[m][k], acc[ai][bj][m][n], 0, 0, 0); __builtin_amdgcn_s_setprio(0); } while (0)
; #define PG8_WAIT_V(n) asm volatile("s_waitcnt vmcnt(" #n ")" ::: "memory")
; #define PG8_WAIT_L(n) asm volatile("s_waitcnt lgkmcnt(" #n ")" ::: "memory")
; template <class Epi, class Sched, bool ALIGN_EPI = false, bool SP2 = false>
; __device__ __forceinline__ void gemm_phase(PG8_LAS unsigned char* lds, const Gemm g, const Sched& S, const Epi& E, int tid_in) {
;     ...
;             const bool last = (t == nt - 2);
;             const char* a1 = cA + (size_t)(t + 1) * kstep;
;             const char* a2 = last ? nA : cA + (size_t)(t + 2) * kstep; const char* b2 = last ? nB : cB + (size_t)(t + 2) * kstep;
;             const char* a3 = a2 + kstep; const char* b3 = b2 + kstep;
;             if (last && has_next) S.a_ready(nxt);
;             if constexpr (SP2) {
;             PG8_LDB(B0, 0, 0); PG8_LDB(B1, 0, 1); PG8_SCHED; PG8_LDA(At, 0, 0); PG8_STAGE(PG8_SA(1, 1), a1 + hstepA, voffA);
;             PG8_WAIT_V(8); PG8_WAIT_L(0); PG8_BAR; PG8_MMA(0, 0, At, B0); PG8_MMA(0, 1, At, B1); PG8_BAR; PG8_SCHED;
;             PG8_LDA(At, 0, 1); PG8_STAGE(PG8_SB(0, 0), b2, voffB); PG8_STAGE(PG8_SB(0, 1), b2 + hstep, voffB); PG8_STAGE(PG8_SA(0, 0), a2, voffA);
;             PG8_WAIT_V(8); PG8_WAIT_L(0); PG8_BAR; PG8_MMA(1, 0, At, B0); PG8_MMA(1, 1, At, B1); PG8_BAR; PG8_SCHED;
.LBB0_1283:
	s_add_u32 s14, s12, 0xfffc0080
	s_addc_u32 s15, s13, -1
	s_add_i32 s60, 0, 0x10000
	s_cmp_eq_u32 s59, 12
	s_cselect_b32 s27, s19, s15
	s_cselect_b32 s26, s55, s14
	s_cselect_b32 s15, s11, s58
	s_cselect_b32 s14, s56, s57
	s_add_i32 s62, 0, 0x14000
	v_add_u32_e32 v124, s60, v226
	v_add_u32_e32 v140, s62, v226
	ds_read_b128 v[112:115], v124
	ds_read_b128 v[116:119], v124 offset:1024
	ds_read_b128 v[120:123], v124 offset:2048
	ds_read_b128 v[124:127], v124 offset:3072
	ds_read_b128 v[128:131], v140
	ds_read_b128 v[132:135], v140 offset:1024
	ds_read_b128 v[136:139], v140 offset:2048
	ds_read_b128 v[140:143], v140 offset:3072
	s_add_i32 m0, s35, 0xc000
	ds_read_b128 v[144:147], v227
	ds_read_b128 v[148:151], v227 offset:1024
	ds_read_b128 v[152:155], v227 offset:2048
	ds_read_b128 v[156:159], v227 offset:3072
	ds_read_b128 v[176:179], v227 offset:4096
	ds_read_b128 v[180:183], v227 offset:5120
	ds_read_b128 v[208:211], v227 offset:6144
	global_load_lds_dwordx4 v206, s[12:13]
	s_add_i32 m0, s35, 0xe000
	ds_read_b128 v[212:215], v227 offset:7168
	global_load_lds_dwordx4 v204, s[12:13]
	s_waitcnt vmcnt(8)
	s_waitcnt lgkmcnt(0)
	s_barrier
	s_setprio 1
	s_waitcnt lgkmcnt(0)
	v_mfma_f32_16x16x32_bf16 v[172:175], v[112:115], v[144:147], v[172:175]
	v_mfma_f32_16x16x32_bf16 v[168:171], v[120:123], v[144:147], v[168:171]
	v_mfma_f32_16x16x32_bf16 v[108:111], v[112:115], v[152:155], v[108:111]
	v_mfma_f32_16x16x32_bf16 v[104:107], v[120:123], v[152:155], v[104:107]
	v_mfma_f32_16x16x32_bf16 v[92:95], v[112:115], v[176:179], v[92:95]
	v_mfma_f32_16x16x32_bf16 v[88:91], v[120:123], v[176:179], v[88:91]
	v_mfma_f32_16x16x32_bf16 v[76:79], v[112:115], v[208:211], v[76:79]
	v_mfma_f32_16x16x32_bf16 v[72:75], v[120:123], v[208:211], v[72:75]
	v_mfma_f32_16x16x32_bf16 v[172:175], v[116:119], v[148:151], v[172:175]
	v_mfma_f32_16x16x32_bf16 v[168:171], v[124:127], v[148:151], v[168:171]
	v_mfma_f32_16x16x32_bf16 v[108:111], v[116:119], v[156:159], v[108:111]
	v_mfma_f32_16x16x32_bf16 v[104:107], v[124:127], v[156:159], v[104:107]
	v_mfma_f32_16x16x32_bf16 v[92:95], v[116:119], v[180:183], v[92:95]
	v_mfma_f32_16x16x32_bf16 v[88:91], v[124:127], v[180:183], v[88:91]
	v_mfma_f32_16x16x32_bf16 v[76:79], v[116:119], v[212:215], v[76:79]
	v_mfma_f32_16x16x32_bf16 v[72:75], v[124:127], v[212:215], v[72:75]
	s_setprio 0
	s_setprio 1
	v_mfma_f32_16x16x32_bf16 v[164:167], v[128:131], v[144:147], v[164:167]
	v_mfma_f32_16x16x32_bf16 v[100:103], v[128:131], v[152:155], v[100:103]
	v_mfma_f32_16x16x32_bf16 v[96:99], v[136:139], v[152:155], v[96:99]
	v_mfma_f32_16x16x32_bf16 v[84:87], v[128:131], v[176:179], v[84:87]
	v_mfma_f32_16x16x32_bf16 v[80:83], v[136:139], v[176:179], v[80:83]
	v_mfma_f32_16x16x32_bf16 v[68:71], v[128:131], v[208:211], v[68:71]
	v_mfma_f32_16x16x32_bf16 v[64:67], v[136:139], v[208:211], v[64:67]
	v_mfma_f32_16x16x32_bf16 v[164:167], v[132:135], v[148:151], v[164:167]
	v_mfma_f32_16x16x32_bf16 v[144:147], v[136:139], v[144:147], v[160:163]
	v_mfma_f32_16x16x32_bf16 v[100:103], v[132:135], v[156:159], v[100:103]
	v_mfma_f32_16x16x32_bf16 v[96:99], v[140:143], v[156:159], v[96:99]
	v_mfma_f32_16x16x32_bf16 v[84:87], v[132:135], v[180:183], v[84:87]
	v_mfma_f32_16x16x32_bf16 v[80:83], v[140:143], v[180:183], v[80:83]
	v_mfma_f32_16x16x32_bf16 v[68:71], v[132:135], v[212:215], v[68:71]
	v_mfma_f32_16x16x32_bf16 v[64:67], v[140:143], v[212:215], v[64:67]
	v_mfma_f32_16x16x32_bf16 v[144:147], v[140:143], v[148:151], v[144:147]
	s_setprio 0
	s_barrier
	s_add_i32 s60, s60, s34
	s_mov_b32 m0, s60
	ds_read_b128 v[148:151], v227 offset:16384
	ds_read_b128 v[152:155], v227 offset:17408
	ds_read_b128 v[156:159], v227 offset:18432
	ds_read_b128 v[160:163], v227 offset:19456
	ds_read_b128 v[176:179], v227 offset:20480
	global_load_lds_dwordx4 v190, s[14:15]
	s_add_i32 m0, s60, 0x2000
	s_add_u32 s60, s14, 0x40000
	s_addc_u32 s61, s15, 0
	s_add_i32 s62, s62, s34
	global_load_lds_dwordx4 v184, s[14:15]
	s_mov_b32 m0, s62
	s_mov_b64 s[100:101], s[26:27]
	global_load_lds_dwordx4 v190, s[60:61]
	s_add_i32 m0, s62, 0x2000
	ds_read_b128 v[180:183], v227 offset:21504
	global_load_lds_dwordx4 v184, s[60:61]
	s_mov_b32 m0, s35
	ds_read_b128 v[208:211], v227 offset:22528
	global_load_lds_dwordx4 v188, s[100:101]
	s_mov_b32 m0, s46
	ds_read_b128 v[212:215], v227 offset:23552
	global_load_lds_dwordx4 v186, s[100:101]
	s_waitcnt vmcnt(8)
	s_waitcnt lgkmcnt(0)
	s_barrier
	s_setprio 1
	s_waitcnt lgkmcnt(0)
	v_mfma_f32_16x16x32_bf16 v[60:63], v[112:115], v[148:151], v[60:63]
	v_mfma_f32_16x16x32_bf16 v[56:59], v[120:123], v[148:151], v[56:59]
	v_mfma_f32_16x16x32_bf16 v[44:47], v[112:115], v[156:159], v[44:47]
	v_mfma_f32_16x16x32_bf16 v[40:43], v[120:123], v[156:159], v[40:43]
	v_mfma_f32_16x16x32_bf16 v[28:31], v[112:115], v[176:179], v[28:31]
	v_mfma_f32_16x16x32_bf16 v[24:27], v[120:123], v[176:179], v[24:27]
	v_mfma_f32_16x16x32_bf16 v[12:15], v[112:115], v[208:211], v[12:15]
	v_mfma_f32_16x16x32_bf16 v[8:11], v[120:123], v[208:211], v[8:11]
	v_mfma_f32_16x16x32_bf16 v[60:63], v[116:119], v[152:155], v[60:63]
	v_mfma_f32_16x16x32_bf16 v[56:59], v[124:127], v[152:155], v[56:59]
	v_mfma_f32_16x16x32_bf16 v[44:47], v[116:119], v[160:163], v[44:47]
	v_mfma_f32_16x16x32_bf16 v[40:43], v[124:127], v[160:163], v[40:43]
	v_mfma_f32_16x16x32_bf16 v[28:31], v[116:119], v[180:183], v[28:31]
	v_mfma_f32_16x16x32_bf16 v[24:27], v[124:127], v[180:183], v[24:27]
	v_mfma_f32_16x16x32_bf16 v[12:15], v[116:119], v[212:215], v[12:15]
	v_mfma_f32_16x16x32_bf16 v[8:11], v[124:127], v[212:215], v[8:11]
	s_setprio 0
	s_setprio 1
	v_mfma_f32_16x16x32_bf16 v[52:55], v[128:131], v[148:151], v[52:55]
	v_mfma_f32_16x16x32_bf16 v[48:51], v[136:139], v[148:151], v[48:51]
	v_mfma_f32_16x16x32_bf16 v[36:39], v[128:131], v[156:159], v[36:39]
	v_mfma_f32_16x16x32_bf16 v[32:35], v[136:139], v[156:159], v[32:35]
	v_mfma_f32_16x16x32_bf16 v[20:23], v[128:131], v[176:179], v[20:23]
	v_mfma_f32_16x16x32_bf16 v[16:19], v[136:139], v[176:179], v[16:19]
	v_mfma_f32_16x16x32_bf16 v[4:7], v[128:131], v[208:211], v[4:7]
	v_mfma_f32_16x16x32_bf16 v[0:3], v[136:139], v[208:211], v[0:3]
	v_mfma_f32_16x16x32_bf16 v[52:55], v[132:135], v[152:155], v[52:55]
	v_mfma_f32_16x16x32_bf16 v[48:51], v[140:143], v[152:155], v[48:51]
	v_mfma_f32_16x16x32_bf16 v[36:39], v[132:135], v[160:163], v[36:39]
	v_mfma_f32_16x16x32_bf16 v[32:35], v[140:143], v[160:163], v[32:35]
	v_mfma_f32_16x16x32_bf16 v[20:23], v[132:135], v[180:183], v[20:23]
	v_mfma_f32_16x16x32_bf16 v[16:19], v[140:143], v[180:183], v[16:19]
	v_mfma_f32_16x16x32_bf16 v[4:7], v[132:135], v[212:215], v[4:7]
	v_mfma_f32_16x16x32_bf16 v[0:3], v[140:143], v[212:215], v[0:3]
	s_setprio 0
	s_barrier
; #define PG8_STAGE(bufoff, gbase, voff) do { _Pragma("unroll") for (int _i = 0; _i < 2; ++_i) \
;         __builtin_amdgcn_global_load_lds((const unsigned*)((const char*)(gbase) + (voff)[_i]), (PG8_LAS unsigned*)(lds + (bufoff) + ldsw + _i * 8192), 16, 0, 0); } while (0)
; #define PG8_LDA(dst, b, h) do { _Pragma("unroll") for (int m = 0; m < 4; ++m) _Pragma("unroll") for (int k = 0; k < 2; ++k) dst[m][k] = *(const PG8_LAS bf16x8*)(lds + PG8_SA(b, h) + aoff + m * 2048 + k * 1024); } while (0)
; #define PG8_LDB(dst, b, h) do { _Pragma("unroll") for (int n = 0; n < 2; ++n) _Pragma("unroll") for (int k = 0; k < 2; ++k) dst[n][k] = *(const PG8_LAS bf16x8*)(lds + PG8_SB(b, h) + boff + n * 2048 + k * 1024); } while (0)
; #define PG8_MMA(ai, bj, At, Bt) do { __builtin_amdgcn_s_setprio(1); _Pragma("unroll") for (int m = 0; m < 4; ++m) _Pragma("unroll") for (int n = 0; n < 2; ++n) _Pragma("unroll") for (int k = 0; k < 2; ++k) \
;         acc[ai][bj][m][n] = __builtin_amdgcn_mfma_f32_16x16x32_bf16(Bt[n][k], At[m][k], acc[ai][bj][m][n], 0, 0, 0); __builtin_amdgcn_s_setprio(0); } while (0)
; #define PG8_WAIT_V(n) asm volatile("s_waitcnt vmcnt(" #n ")" ::: "memory")
; #define PG8_WAIT_L(n) asm volatile("s_waitcnt lgkmcnt(" #n ")" ::: "memory")
; #define PG8_BAR __builtin_amdgcn_s_barrier()
; #define PG8_SCHED __builtin_amdgcn_sched_barrier(0)
; template <class Epi, class Sched, bool ALIGN_EPI = false, bool SP2 = false>
; __device__ __forceinline__ void gemm_phase(PG8_LAS unsigned char* lds, const Gemm g, const Sched& S, const Epi& E, int tid_in) {
;     ...
;             PG8_LDB(B0, 1, 0); PG8_LDB(B1, 1, 1); PG8_SCHED; PG8_LDA(At, 1, 0); PG8_STAGE(PG8_SA(0, 1), a2 + hstepA, voffA);
;             PG8_WAIT_V(8); PG8_WAIT_L(0); PG8_BAR; PG8_MMA(0, 0, At, B0); PG8_MMA(0, 1, At, B1); PG8_BAR; PG8_SCHED;
;             PG8_LDA(At, 1, 1); PG8_STAGE(PG8_SB(1, 0), b3, voffB); PG8_STAGE(PG8_SB(1, 1), b3 + hstep, voffB); PG8_STAGE(PG8_SA(1, 0), a3, voffA);
;             PG8_WAIT_V(8); PG8_WAIT_L(0); PG8_BAR; PG8_MMA(1, 0, At, B0); PG8_MMA(1, 1, At, B1); PG8_BAR; PG8_SCHED;
;     ...
;         if constexpr (ALIGN_EPI) { if (wr == 0) PG8_BAR; }
	s_add_i32 s60, 0, 0x18000
	s_add_i32 s61, 0, 0x1c000
	v_add_u32_e32 v124, s60, v226
	v_add_u32_e32 v140, s61, v226
	ds_read_b128 v[112:115], v124
	ds_read_b128 v[116:119], v124 offset:1024
	ds_read_b128 v[120:123], v124 offset:2048
	ds_read_b128 v[124:127], v124 offset:3072
	ds_read_b128 v[128:131], v140
	ds_read_b128 v[132:135], v140 offset:1024
	ds_read_b128 v[136:139], v140 offset:2048
	ds_read_b128 v[140:143], v140 offset:3072
	s_add_u32 s26, s26, 0x40000
	s_addc_u32 s27, s27, 0
	s_mov_b32 m0, s47
	ds_read_b128 v[148:151], v227 offset:32768
	ds_read_b128 v[152:155], v227 offset:33792
	ds_read_b128 v[156:159], v227 offset:34816
	ds_read_b128 v[176:179], v227 offset:35840
	ds_read_b128 v[180:183], v227 offset:36864
	ds_read_b128 v[208:211], v227 offset:37888
	ds_read_b128 v[212:215], v227 offset:38912
	global_load_lds_dwordx4 v188, s[26:27]
	s_mov_b32 m0, s49
	ds_read_b128 v[216:219], v227 offset:39936
	global_load_lds_dwordx4 v186, s[26:27]
	s_waitcnt vmcnt(8)
	s_waitcnt lgkmcnt(0)
	s_barrier
	s_setprio 1
	s_waitcnt lgkmcnt(0)
	v_mfma_f32_16x16x32_bf16 v[160:163], v[112:115], v[148:151], v[172:175]
	v_mfma_f32_16x16x32_bf16 v[172:175], v[116:119], v[152:155], v[160:163]
	v_mfma_f32_16x16x32_bf16 v[160:163], v[120:123], v[148:151], v[168:171]
	v_mfma_f32_16x16x32_bf16 v[108:111], v[112:115], v[156:159], v[108:111]
	v_mfma_f32_16x16x32_bf16 v[104:107], v[120:123], v[156:159], v[104:107]
	v_mfma_f32_16x16x32_bf16 v[92:95], v[112:115], v[180:183], v[92:95]
	v_mfma_f32_16x16x32_bf16 v[88:91], v[120:123], v[180:183], v[88:91]
	v_mfma_f32_16x16x32_bf16 v[76:79], v[112:115], v[212:215], v[76:79]
	v_mfma_f32_16x16x32_bf16 v[72:75], v[120:123], v[212:215], v[72:75]
	v_mfma_f32_16x16x32_bf16 v[168:171], v[124:127], v[152:155], v[160:163]
	v_mfma_f32_16x16x32_bf16 v[108:111], v[116:119], v[176:179], v[108:111]
	v_mfma_f32_16x16x32_bf16 v[104:107], v[124:127], v[176:179], v[104:107]
	v_mfma_f32_16x16x32_bf16 v[92:95], v[116:119], v[208:211], v[92:95]
	v_mfma_f32_16x16x32_bf16 v[88:91], v[124:127], v[208:211], v[88:91]
	v_mfma_f32_16x16x32_bf16 v[76:79], v[116:119], v[216:219], v[76:79]
	v_mfma_f32_16x16x32_bf16 v[72:75], v[124:127], v[216:219], v[72:75]
	s_setprio 0
	s_setprio 1
	v_mfma_f32_16x16x32_bf16 v[160:163], v[128:131], v[148:151], v[164:167]
	v_mfma_f32_16x16x32_bf16 v[144:147], v[136:139], v[148:151], v[144:147]
	v_mfma_f32_16x16x32_bf16 v[100:103], v[128:131], v[156:159], v[100:103]
	v_mfma_f32_16x16x32_bf16 v[96:99], v[136:139], v[156:159], v[96:99]
	v_mfma_f32_16x16x32_bf16 v[84:87], v[128:131], v[180:183], v[84:87]
	v_mfma_f32_16x16x32_bf16 v[80:83], v[136:139], v[180:183], v[80:83]
	v_mfma_f32_16x16x32_bf16 v[68:71], v[128:131], v[212:215], v[68:71]
	v_mfma_f32_16x16x32_bf16 v[64:67], v[136:139], v[212:215], v[64:67]
	v_mfma_f32_16x16x32_bf16 v[164:167], v[132:135], v[152:155], v[160:163]
	v_mfma_f32_16x16x32_bf16 v[160:163], v[140:143], v[152:155], v[144:147]
	v_mfma_f32_16x16x32_bf16 v[100:103], v[132:135], v[176:179], v[100:103]
	v_mfma_f32_16x16x32_bf16 v[96:99], v[140:143], v[176:179], v[96:99]
	v_mfma_f32_16x16x32_bf16 v[84:87], v[132:135], v[208:211], v[84:87]
	v_mfma_f32_16x16x32_bf16 v[80:83], v[140:143], v[208:211], v[80:83]
	v_mfma_f32_16x16x32_bf16 v[68:71], v[132:135], v[216:219], v[68:71]
	v_mfma_f32_16x16x32_bf16 v[64:67], v[140:143], v[216:219], v[64:67]
	s_setprio 0
	s_barrier
	s_add_i32 s26, s60, s34
	s_mov_b32 m0, s26
	ds_read_b128 v[144:147], v227 offset:49152
	ds_read_b128 v[148:151], v227 offset:50176
	ds_read_b128 v[152:155], v227 offset:51200
	ds_read_b128 v[156:159], v227 offset:52224
	s_add_u32 s14, s14, 0x80
	s_addc_u32 s15, s15, 0
	global_load_lds_dwordx4 v190, s[14:15]
	s_add_i32 m0, s26, 0x2000
	ds_read_b128 v[176:179], v227 offset:53248
	global_load_lds_dwordx4 v184, s[14:15]
	s_add_u32 s14, s14, 0x40000
	s_addc_u32 s15, s15, 0
	s_add_i32 s26, s61, s34
	s_mov_b32 m0, s26
	ds_read_b128 v[180:183], v227 offset:54272
	global_load_lds_dwordx4 v190, s[14:15]
	s_add_i32 m0, s26, 0x2000
	ds_read_b128 v[208:211], v227 offset:55296
	global_load_lds_dwordx4 v184, s[14:15]
	s_mov_b32 m0, s52
	s_nop 0
	s_add_u32 s100, s100, 0x80
	s_addc_u32 s101, s101, 0
	global_load_lds_dwordx4 v188, s[100:101]
	s_mov_b32 m0, s53
	ds_read_b128 v[212:215], v227 offset:56320
	global_load_lds_dwordx4 v186, s[100:101]
	s_waitcnt vmcnt(8)
	s_waitcnt lgkmcnt(0)
	s_barrier
	s_setprio 1
	s_waitcnt lgkmcnt(0)
	v_mfma_f32_16x16x32_bf16 v[60:63], v[112:115], v[144:147], v[60:63]
	v_mfma_f32_16x16x32_bf16 v[56:59], v[120:123], v[144:147], v[56:59]
	v_mfma_f32_16x16x32_bf16 v[44:47], v[112:115], v[152:155], v[44:47]
	v_mfma_f32_16x16x32_bf16 v[40:43], v[120:123], v[152:155], v[40:43]
	v_mfma_f32_16x16x32_bf16 v[28:31], v[112:115], v[176:179], v[28:31]
	v_mfma_f32_16x16x32_bf16 v[24:27], v[120:123], v[176:179], v[24:27]
	v_mfma_f32_16x16x32_bf16 v[12:15], v[112:115], v[208:211], v[12:15]
	v_mfma_f32_16x16x32_bf16 v[8:11], v[120:123], v[208:211], v[8:11]
	v_mfma_f32_16x16x32_bf16 v[60:63], v[116:119], v[148:151], v[60:63]
	v_mfma_f32_16x16x32_bf16 v[56:59], v[124:127], v[148:151], v[56:59]
	v_mfma_f32_16x16x32_bf16 v[44:47], v[116:119], v[156:159], v[44:47]
	v_mfma_f32_16x16x32_bf16 v[40:43], v[124:127], v[156:159], v[40:43]
	v_mfma_f32_16x16x32_bf16 v[28:31], v[116:119], v[180:183], v[28:31]
	v_mfma_f32_16x16x32_bf16 v[24:27], v[124:127], v[180:183], v[24:27]
	v_mfma_f32_16x16x32_bf16 v[12:15], v[116:119], v[212:215], v[12:15]
	v_mfma_f32_16x16x32_bf16 v[8:11], v[124:127], v[212:215], v[8:11]
	s_setprio 0
	s_setprio 1
	v_mfma_f32_16x16x32_bf16 v[52:55], v[128:131], v[144:147], v[52:55]
	v_mfma_f32_16x16x32_bf16 v[48:51], v[136:139], v[144:147], v[48:51]
	v_mfma_f32_16x16x32_bf16 v[36:39], v[128:131], v[152:155], v[36:39]
	v_mfma_f32_16x16x32_bf16 v[32:35], v[136:139], v[152:155], v[32:35]
	v_mfma_f32_16x16x32_bf16 v[20:23], v[128:131], v[176:179], v[20:23]
	v_mfma_f32_16x16x32_bf16 v[16:19], v[136:139], v[176:179], v[16:19]
	v_mfma_f32_16x16x32_bf16 v[4:7], v[128:131], v[208:211], v[4:7]
	v_mfma_f32_16x16x32_bf16 v[0:3], v[136:139], v[208:211], v[0:3]
	v_mfma_f32_16x16x32_bf16 v[52:55], v[132:135], v[148:151], v[52:55]
	v_mfma_f32_16x16x32_bf16 v[48:51], v[140:143], v[148:151], v[48:51]
	v_mfma_f32_16x16x32_bf16 v[36:39], v[132:135], v[156:159], v[36:39]
	v_mfma_f32_16x16x32_bf16 v[32:35], v[140:143], v[156:159], v[32:35]
	v_mfma_f32_16x16x32_bf16 v[20:23], v[132:135], v[180:183], v[20:23]
	v_mfma_f32_16x16x32_bf16 v[16:19], v[140:143], v[180:183], v[16:19]
	v_mfma_f32_16x16x32_bf16 v[4:7], v[132:135], v[212:215], v[4:7]
	v_mfma_f32_16x16x32_bf16 v[0:3], v[140:143], v[212:215], v[0:3]
	s_setprio 0
	s_barrier
	s_add_i32 s59, s59, 2
	s_add_u32 s57, s57, 0x100
	s_addc_u32 s58, s58, 0
	s_add_u32 s12, s12, 0x100
	s_addc_u32 s13, s13, 0
	s_cmp_gt_u32 s59, 13
	s_cbranch_scc0 .LBB0_1283
	s_and_b64 vcc, exec, s[8:9]
	s_cbranch_vccz .LBB0_1286
	s_barrier

; #define PG8_STAGE(bufoff, gbase, voff) do { _Pragma("unroll") for (int _i = 0; _i < 2; ++_i) \
;         __builtin_amdgcn_global_load_lds((const unsigned*)((const char*)(gbase) + (voff)[_i]), (PG8_LAS unsigned*)(lds + (bufoff) + ldsw + _i * 8192), 16, 0, 0); } while (0)
; #define PG8_LDA(dst, b, h) do { _Pragma("unroll") for (int m = 0; m < 4; ++m) _Pragma("unroll") for (int k = 0; k < 2; ++k) dst[m][k] = *(const PG8_LAS bf16x8*)(lds + PG8_SA(b, h) + aoff + m * 2048 + k * 1024); } while (0)
; #define PG8_LDB(dst, b, h) do { _Pragma("unroll") for (int n = 0; n < 2; ++n) _Pragma("unroll") for (int k = 0; k < 2; ++k) dst[n][k] = *(const PG8_LAS bf16x8*)(lds + PG8_SB(b, h) + boff + n * 2048 + k * 1024); } while (0)
; #define PG8_MMA(ai, bj, At, Bt) do { __builtin_amdgcn_s_setprio(1); _Pragma("unroll") for (int m = 0; m < 4; ++m) _Pragma("unroll") for (int n = 0; n < 2; ++n) _Pragma("unroll") for (int k = 0; k < 2; ++k) \
;         acc[ai][bj][m][n] = __builtin_amdgcn_mfma_f32_16x16x32_bf16(Bt[n][k], At[m][k], acc[ai][bj][m][n], 0, 0, 0); __builtin_amdgcn_s_setprio(0); } while (0)
; #define PG8_WAIT_V(n) asm volatile("s_waitcnt vmcnt(" #n ")" ::: "memory")
; #define PG8_WAIT_L(n) asm volatile("s_waitcnt lgkmcnt(" #n ")" ::: "memory")
; template <class Epi, class Sched, bool ALIGN_EPI = false, bool SP2 = false>
; __device__ __forceinline__ void gemm_phase(PG8_LAS unsigned char* lds, const Gemm g, const Sched& S, const Epi& E, int tid_in) {
;     ...
;             const bool last = (t == nt - 2);
;             const char* a1 = cA + (size_t)(t + 1) * kstep;
;             const char* a2 = last ? nA : cA + (size_t)(t + 2) * kstep; const char* b2 = last ? nB : cB + (size_t)(t + 2) * kstep;
;             const char* a3 = a2 + kstep; const char* b3 = b2 + kstep;
;             if (last && has_next) S.a_ready(nxt);
;             if constexpr (SP2) {
;             PG8_LDB(B0, 0, 0); PG8_LDB(B1, 0, 1); PG8_SCHED; PG8_LDA(At, 0, 0); PG8_STAGE(PG8_SA(1, 1), a1 + hstepA, voffA);
;             PG8_WAIT_V(8); PG8_WAIT_L(0); PG8_BAR; PG8_MMA(0, 0, At, B0); PG8_MMA(0, 1, At, B1); PG8_BAR; PG8_SCHED;
;             PG8_LDA(At, 0, 1); PG8_STAGE(PG8_SB(0, 0), b2, voffB); PG8_STAGE(PG8_SB(0, 1), b2 + hstep, voffB); PG8_STAGE(PG8_SA(0, 0), a2, voffA);
;             PG8_WAIT_V(8); PG8_WAIT_L(0); PG8_BAR; PG8_MMA(1, 0, At, B0); PG8_MMA(1, 1, At, B1); PG8_BAR; PG8_SCHED;
.LBB0_1385:
	s_add_u32 s12, s2, 0xfffc0080
	s_addc_u32 s13, s3, -1
	s_add_i32 s58, 0, 0x10000
	s_cmp_eq_u32 s57, 12
	s_cselect_b32 s15, s21, s13
	s_cselect_b32 s14, s53, s12
	v_add_u32_e32 v140, s58, v145
	s_cselect_b32 s13, s19, s56
	s_cselect_b32 s12, s54, s55
	s_add_i32 s60, 0, 0x14000
	ds_read_b128 v[148:151], v140
	ds_read_b128 v[152:155], v140 offset:1024
	ds_read_b128 v[156:159], v140 offset:2048
	ds_read_b128 v[160:163], v140 offset:3072
	v_add_u32_e32 v140, s60, v145
	ds_read_b128 v[164:167], v140
	ds_read_b128 v[168:171], v140 offset:1024
	ds_read_b128 v[172:175], v140 offset:2048
	ds_read_b128 v[176:179], v140 offset:3072
	s_add_i32 m0, s45, 0xc000
	ds_read_b128 v[180:183], v146
	ds_read_b128 v[184:187], v146 offset:1024
	ds_read_b128 v[200:203], v146 offset:2048
	ds_read_b128 v[204:207], v146 offset:3072
	ds_read_b128 v[208:211], v146 offset:4096
	ds_read_b128 v[212:215], v146 offset:5120
	ds_read_b128 v[216:219], v146 offset:6144
	global_load_lds_dwordx4 v138, s[2:3]
	s_add_i32 m0, s45, 0xe000
	ds_read_b128 v[226:229], v146 offset:7168
	global_load_lds_dwordx4 v136, s[2:3]
	s_waitcnt vmcnt(8)
	s_waitcnt lgkmcnt(0)
	s_barrier
	s_setprio 1
	s_waitcnt lgkmcnt(0)
	v_mfma_f32_16x16x32_bf16 v[124:127], v[148:151], v[180:183], v[124:127]
	v_mfma_f32_16x16x32_bf16 v[116:119], v[156:159], v[180:183], v[116:119]
	v_mfma_f32_16x16x32_bf16 v[108:111], v[148:151], v[200:203], v[108:111]
	v_mfma_f32_16x16x32_bf16 v[100:103], v[156:159], v[200:203], v[100:103]
	v_mfma_f32_16x16x32_bf16 v[92:95], v[148:151], v[208:211], v[92:95]
	v_mfma_f32_16x16x32_bf16 v[84:87], v[156:159], v[208:211], v[84:87]
	v_mfma_f32_16x16x32_bf16 v[76:79], v[148:151], v[216:219], v[76:79]
	v_mfma_f32_16x16x32_bf16 v[68:71], v[156:159], v[216:219], v[68:71]
	v_mfma_f32_16x16x32_bf16 v[124:127], v[152:155], v[184:187], v[124:127]
	v_mfma_f32_16x16x32_bf16 v[116:119], v[160:163], v[184:187], v[116:119]
	v_mfma_f32_16x16x32_bf16 v[108:111], v[152:155], v[204:207], v[108:111]
	v_mfma_f32_16x16x32_bf16 v[100:103], v[160:163], v[204:207], v[100:103]
	v_mfma_f32_16x16x32_bf16 v[92:95], v[152:155], v[212:215], v[92:95]
	v_mfma_f32_16x16x32_bf16 v[84:87], v[160:163], v[212:215], v[84:87]
	v_mfma_f32_16x16x32_bf16 v[76:79], v[152:155], v[226:229], v[76:79]
	v_mfma_f32_16x16x32_bf16 v[68:71], v[160:163], v[226:229], v[68:71]
	s_setprio 0
	s_setprio 1
	v_mfma_f32_16x16x32_bf16 v[120:123], v[164:167], v[180:183], v[120:123]
	v_mfma_f32_16x16x32_bf16 v[112:115], v[172:175], v[180:183], v[112:115]
	v_mfma_f32_16x16x32_bf16 v[104:107], v[164:167], v[200:203], v[104:107]
	v_mfma_f32_16x16x32_bf16 v[96:99], v[172:175], v[200:203], v[96:99]
	v_mfma_f32_16x16x32_bf16 v[88:91], v[164:167], v[208:211], v[88:91]
	v_mfma_f32_16x16x32_bf16 v[80:83], v[172:175], v[208:211], v[80:83]
	v_mfma_f32_16x16x32_bf16 v[72:75], v[164:167], v[216:219], v[72:75]
	v_mfma_f32_16x16x32_bf16 v[64:67], v[172:175], v[216:219], v[64:67]
	v_mfma_f32_16x16x32_bf16 v[120:123], v[168:171], v[184:187], v[120:123]
	v_mfma_f32_16x16x32_bf16 v[112:115], v[176:179], v[184:187], v[112:115]
	v_mfma_f32_16x16x32_bf16 v[104:107], v[168:171], v[204:207], v[104:107]
	v_mfma_f32_16x16x32_bf16 v[96:99], v[176:179], v[204:207], v[96:99]
	v_mfma_f32_16x16x32_bf16 v[88:91], v[168:171], v[212:215], v[88:91]
	v_mfma_f32_16x16x32_bf16 v[80:83], v[176:179], v[212:215], v[80:83]
	v_mfma_f32_16x16x32_bf16 v[72:75], v[168:171], v[226:229], v[72:75]
	v_mfma_f32_16x16x32_bf16 v[64:67], v[176:179], v[226:229], v[64:67]
	s_setprio 0
	s_barrier
	s_add_i32 s58, s58, s44
	s_mov_b32 m0, s58
	ds_read_b128 v[180:183], v146 offset:16384
	ds_read_b128 v[184:187], v146 offset:17408
	ds_read_b128 v[200:203], v146 offset:18432
	ds_read_b128 v[204:207], v146 offset:19456
	ds_read_b128 v[208:211], v146 offset:20480
	global_load_lds_dwordx4 v132, s[12:13]
	s_add_i32 m0, s58, 0x2000
	s_add_u32 s58, s12, 0x40000
	s_addc_u32 s59, s13, 0
	s_add_i32 s60, s60, s44
	global_load_lds_dwordx4 v128, s[12:13]
	s_mov_b32 m0, s60
	s_mov_b64 s[100:101], s[14:15]
	global_load_lds_dwordx4 v132, s[58:59]
	s_add_i32 m0, s60, 0x2000
	ds_read_b128 v[212:215], v146 offset:21504
	global_load_lds_dwordx4 v128, s[58:59]
	s_mov_b32 m0, s45
	ds_read_b128 v[216:219], v146 offset:22528
	global_load_lds_dwordx4 v134, s[100:101]
	s_mov_b32 m0, s46
	ds_read_b128 v[226:229], v146 offset:23552
	global_load_lds_dwordx4 v130, s[100:101]
	s_waitcnt vmcnt(8)
	s_waitcnt lgkmcnt(0)
	s_barrier
	s_setprio 1
	s_waitcnt lgkmcnt(0)
	v_mfma_f32_16x16x32_bf16 v[60:63], v[148:151], v[180:183], v[60:63]
	v_mfma_f32_16x16x32_bf16 v[52:55], v[156:159], v[180:183], v[52:55]
	v_mfma_f32_16x16x32_bf16 v[44:47], v[148:151], v[200:203], v[44:47]
	v_mfma_f32_16x16x32_bf16 v[36:39], v[156:159], v[200:203], v[36:39]
	v_mfma_f32_16x16x32_bf16 v[28:31], v[148:151], v[208:211], v[28:31]
	v_mfma_f32_16x16x32_bf16 v[20:23], v[156:159], v[208:211], v[20:23]
	v_mfma_f32_16x16x32_bf16 v[12:15], v[148:151], v[216:219], v[12:15]
	v_mfma_f32_16x16x32_bf16 v[4:7], v[156:159], v[216:219], v[4:7]
	v_mfma_f32_16x16x32_bf16 v[60:63], v[152:155], v[184:187], v[60:63]
	v_mfma_f32_16x16x32_bf16 v[52:55], v[160:163], v[184:187], v[52:55]
	v_mfma_f32_16x16x32_bf16 v[44:47], v[152:155], v[204:207], v[44:47]
	v_mfma_f32_16x16x32_bf16 v[36:39], v[160:163], v[204:207], v[36:39]
	v_mfma_f32_16x16x32_bf16 v[28:31], v[152:155], v[212:215], v[28:31]
	v_mfma_f32_16x16x32_bf16 v[20:23], v[160:163], v[212:215], v[20:23]
	v_mfma_f32_16x16x32_bf16 v[12:15], v[152:155], v[226:229], v[12:15]
	v_mfma_f32_16x16x32_bf16 v[4:7], v[160:163], v[226:229], v[4:7]
	s_setprio 0
	s_setprio 1
	v_mfma_f32_16x16x32_bf16 v[56:59], v[164:167], v[180:183], v[56:59]
	v_mfma_f32_16x16x32_bf16 v[48:51], v[172:175], v[180:183], v[48:51]
	v_mfma_f32_16x16x32_bf16 v[40:43], v[164:167], v[200:203], v[40:43]
	v_mfma_f32_16x16x32_bf16 v[32:35], v[172:175], v[200:203], v[32:35]
	v_mfma_f32_16x16x32_bf16 v[24:27], v[164:167], v[208:211], v[24:27]
	v_mfma_f32_16x16x32_bf16 v[16:19], v[172:175], v[208:211], v[16:19]
	v_mfma_f32_16x16x32_bf16 v[8:11], v[164:167], v[216:219], v[8:11]
	v_mfma_f32_16x16x32_bf16 v[0:3], v[172:175], v[216:219], v[0:3]
	v_mfma_f32_16x16x32_bf16 v[56:59], v[168:171], v[184:187], v[56:59]
	v_mfma_f32_16x16x32_bf16 v[48:51], v[176:179], v[184:187], v[48:51]
	v_mfma_f32_16x16x32_bf16 v[40:43], v[168:171], v[204:207], v[40:43]
	v_mfma_f32_16x16x32_bf16 v[32:35], v[176:179], v[204:207], v[32:35]
	v_mfma_f32_16x16x32_bf16 v[24:27], v[168:171], v[212:215], v[24:27]
	v_mfma_f32_16x16x32_bf16 v[16:19], v[176:179], v[212:215], v[16:19]
	v_mfma_f32_16x16x32_bf16 v[8:11], v[168:171], v[226:229], v[8:11]
	v_mfma_f32_16x16x32_bf16 v[0:3], v[176:179], v[226:229], v[0:3]
	s_setprio 0
	s_barrier
; #define PG8_STAGE(bufoff, gbase, voff) do { _Pragma("unroll") for (int _i = 0; _i < 2; ++_i) \
;         __builtin_amdgcn_global_load_lds((const unsigned*)((const char*)(gbase) + (voff)[_i]), (PG8_LAS unsigned*)(lds + (bufoff) + ldsw + _i * 8192), 16, 0, 0); } while (0)
; #define PG8_LDA(dst, b, h) do { _Pragma("unroll") for (int m = 0; m < 4; ++m) _Pragma("unroll") for (int k = 0; k < 2; ++k) dst[m][k] = *(const PG8_LAS bf16x8*)(lds + PG8_SA(b, h) + aoff + m * 2048 + k * 1024); } while (0)
; #define PG8_LDB(dst, b, h) do { _Pragma("unroll") for (int n = 0; n < 2; ++n) _Pragma("unroll") for (int k = 0; k < 2; ++k) dst[n][k] = *(const PG8_LAS bf16x8*)(lds + PG8_SB(b, h) + boff + n * 2048 + k * 1024); } while (0)
; #define PG8_MMA(ai, bj, At, Bt) do { __builtin_amdgcn_s_setprio(1); _Pragma("unroll") for (int m = 0; m < 4; ++m) _Pragma("unroll") for (int n = 0; n < 2; ++n) _Pragma("unroll") for (int k = 0; k < 2; ++k) \
;         acc[ai][bj][m][n] = __builtin_amdgcn_mfma_f32_16x16x32_bf16(Bt[n][k], At[m][k], acc[ai][bj][m][n], 0, 0, 0); __builtin_amdgcn_s_setprio(0); } while (0)
; #define PG8_WAIT_V(n) asm volatile("s_waitcnt vmcnt(" #n ")" ::: "memory")
; #define PG8_WAIT_L(n) asm volatile("s_waitcnt lgkmcnt(" #n ")" ::: "memory")
; #define PG8_BAR __builtin_amdgcn_s_barrier()
; #define PG8_SCHED __builtin_amdgcn_sched_barrier(0)
; template <class Epi, class Sched, bool ALIGN_EPI = false, bool SP2 = false>
; __device__ __forceinline__ void gemm_phase(PG8_LAS unsigned char* lds, const Gemm g, const Sched& S, const Epi& E, int tid_in) {
;     ...
;             PG8_LDB(B0, 1, 0); PG8_LDB(B1, 1, 1); PG8_SCHED; PG8_LDA(At, 1, 0); PG8_STAGE(PG8_SA(0, 1), a2 + hstepA, voffA);
;             PG8_WAIT_V(8); PG8_WAIT_L(0); PG8_BAR; PG8_MMA(0, 0, At, B0); PG8_MMA(0, 1, At, B1); PG8_BAR; PG8_SCHED;
;             PG8_LDA(At, 1, 1); PG8_STAGE(PG8_SB(1, 0), b3, voffB); PG8_STAGE(PG8_SB(1, 1), b3 + hstep, voffB); PG8_STAGE(PG8_SA(1, 0), a3, voffA);
;             PG8_WAIT_V(8); PG8_WAIT_L(0); PG8_BAR; PG8_MMA(1, 0, At, B0); PG8_MMA(1, 1, At, B1); PG8_BAR; PG8_SCHED;
	s_add_i32 s58, 0, 0x18000
	v_add_u32_e32 v142, s58, v145
	s_add_i32 s59, 0, 0x1c000
	ds_read_b128 v[148:151], v142
	ds_read_b128 v[152:155], v142 offset:1024
	ds_read_b128 v[156:159], v142 offset:2048
	ds_read_b128 v[160:163], v142 offset:3072
	v_add_u32_e32 v142, s59, v145
	ds_read_b128 v[164:167], v142
	ds_read_b128 v[168:171], v142 offset:1024
	ds_read_b128 v[172:175], v142 offset:2048
	ds_read_b128 v[176:179], v142 offset:3072
	s_add_u32 s14, s14, 0x40000
	s_addc_u32 s15, s15, 0
	s_mov_b32 m0, s47
	ds_read_b128 v[180:183], v146 offset:32768
	ds_read_b128 v[184:187], v146 offset:33792
	ds_read_b128 v[200:203], v146 offset:34816
	ds_read_b128 v[204:207], v146 offset:35840
	ds_read_b128 v[208:211], v146 offset:36864
	ds_read_b128 v[212:215], v146 offset:37888
	ds_read_b128 v[216:219], v146 offset:38912
	global_load_lds_dwordx4 v134, s[14:15]
	s_mov_b32 m0, s49
	ds_read_b128 v[226:229], v146 offset:39936
	global_load_lds_dwordx4 v130, s[14:15]
	s_waitcnt vmcnt(8)
	s_waitcnt lgkmcnt(0)
	s_barrier
	s_setprio 1
	s_waitcnt lgkmcnt(0)
	v_mfma_f32_16x16x32_bf16 v[124:127], v[148:151], v[180:183], v[124:127]
	v_mfma_f32_16x16x32_bf16 v[116:119], v[156:159], v[180:183], v[116:119]
	v_mfma_f32_16x16x32_bf16 v[108:111], v[148:151], v[200:203], v[108:111]
	v_mfma_f32_16x16x32_bf16 v[100:103], v[156:159], v[200:203], v[100:103]
	v_mfma_f32_16x16x32_bf16 v[92:95], v[148:151], v[208:211], v[92:95]
	v_mfma_f32_16x16x32_bf16 v[84:87], v[156:159], v[208:211], v[84:87]
	v_mfma_f32_16x16x32_bf16 v[76:79], v[148:151], v[216:219], v[76:79]
	v_mfma_f32_16x16x32_bf16 v[68:71], v[156:159], v[216:219], v[68:71]
	v_mfma_f32_16x16x32_bf16 v[124:127], v[152:155], v[184:187], v[124:127]
	v_mfma_f32_16x16x32_bf16 v[116:119], v[160:163], v[184:187], v[116:119]
	v_mfma_f32_16x16x32_bf16 v[108:111], v[152:155], v[204:207], v[108:111]
	v_mfma_f32_16x16x32_bf16 v[100:103], v[160:163], v[204:207], v[100:103]
	v_mfma_f32_16x16x32_bf16 v[92:95], v[152:155], v[212:215], v[92:95]
	v_mfma_f32_16x16x32_bf16 v[84:87], v[160:163], v[212:215], v[84:87]
	v_mfma_f32_16x16x32_bf16 v[76:79], v[152:155], v[226:229], v[76:79]
	v_mfma_f32_16x16x32_bf16 v[68:71], v[160:163], v[226:229], v[68:71]
	s_setprio 0
	s_setprio 1
	v_mfma_f32_16x16x32_bf16 v[120:123], v[164:167], v[180:183], v[120:123]
	v_mfma_f32_16x16x32_bf16 v[112:115], v[172:175], v[180:183], v[112:115]
	v_mfma_f32_16x16x32_bf16 v[104:107], v[164:167], v[200:203], v[104:107]
	v_mfma_f32_16x16x32_bf16 v[96:99], v[172:175], v[200:203], v[96:99]
	v_mfma_f32_16x16x32_bf16 v[88:91], v[164:167], v[208:211], v[88:91]
	v_mfma_f32_16x16x32_bf16 v[80:83], v[172:175], v[208:211], v[80:83]
	v_mfma_f32_16x16x32_bf16 v[72:75], v[164:167], v[216:219], v[72:75]
	v_mfma_f32_16x16x32_bf16 v[64:67], v[172:175], v[216:219], v[64:67]
	v_mfma_f32_16x16x32_bf16 v[120:123], v[168:171], v[184:187], v[120:123]
	v_mfma_f32_16x16x32_bf16 v[112:115], v[176:179], v[184:187], v[112:115]
	v_mfma_f32_16x16x32_bf16 v[104:107], v[168:171], v[204:207], v[104:107]
	v_mfma_f32_16x16x32_bf16 v[96:99], v[176:179], v[204:207], v[96:99]
	v_mfma_f32_16x16x32_bf16 v[88:91], v[168:171], v[212:215], v[88:91]
	v_mfma_f32_16x16x32_bf16 v[80:83], v[176:179], v[212:215], v[80:83]
	v_mfma_f32_16x16x32_bf16 v[72:75], v[168:171], v[226:229], v[72:75]
	v_mfma_f32_16x16x32_bf16 v[64:67], v[176:179], v[226:229], v[64:67]
	s_setprio 0
	s_barrier
	s_add_i32 s14, s58, s44
	s_mov_b32 m0, s14
	ds_read_b128 v[180:183], v146 offset:49152
	ds_read_b128 v[184:187], v146 offset:50176
	ds_read_b128 v[200:203], v146 offset:51200
	ds_read_b128 v[204:207], v146 offset:52224
	s_add_u32 s12, s12, 0x80
	s_addc_u32 s13, s13, 0
	global_load_lds_dwordx4 v132, s[12:13]
	s_add_i32 m0, s14, 0x2000
	ds_read_b128 v[208:211], v146 offset:53248
	global_load_lds_dwordx4 v128, s[12:13]
	s_add_u32 s12, s12, 0x40000
	s_addc_u32 s13, s13, 0
	s_add_i32 s14, s59, s44
	s_mov_b32 m0, s14
	ds_read_b128 v[212:215], v146 offset:54272
	global_load_lds_dwordx4 v132, s[12:13]
	s_add_i32 m0, s14, 0x2000
	ds_read_b128 v[216:219], v146 offset:55296
	global_load_lds_dwordx4 v128, s[12:13]
	s_mov_b32 m0, s50
	s_nop 0
	s_add_u32 s100, s100, 0x80
	s_addc_u32 s101, s101, 0
	global_load_lds_dwordx4 v134, s[100:101]
	s_mov_b32 m0, s51
	ds_read_b128 v[226:229], v146 offset:56320
	global_load_lds_dwordx4 v130, s[100:101]
	s_waitcnt vmcnt(8)
	s_waitcnt lgkmcnt(0)
	s_barrier
	s_setprio 1
	s_waitcnt lgkmcnt(0)
	v_mfma_f32_16x16x32_bf16 v[60:63], v[148:151], v[180:183], v[60:63]
	v_mfma_f32_16x16x32_bf16 v[52:55], v[156:159], v[180:183], v[52:55]
	v_mfma_f32_16x16x32_bf16 v[44:47], v[148:151], v[200:203], v[44:47]
	v_mfma_f32_16x16x32_bf16 v[36:39], v[156:159], v[200:203], v[36:39]
	v_mfma_f32_16x16x32_bf16 v[28:31], v[148:151], v[208:211], v[28:31]
	v_mfma_f32_16x16x32_bf16 v[20:23], v[156:159], v[208:211], v[20:23]
	v_mfma_f32_16x16x32_bf16 v[12:15], v[148:151], v[216:219], v[12:15]
	v_mfma_f32_16x16x32_bf16 v[4:7], v[156:159], v[216:219], v[4:7]
	v_mfma_f32_16x16x32_bf16 v[60:63], v[152:155], v[184:187], v[60:63]
	v_mfma_f32_16x16x32_bf16 v[52:55], v[160:163], v[184:187], v[52:55]
	v_mfma_f32_16x16x32_bf16 v[44:47], v[152:155], v[204:207], v[44:47]
	v_mfma_f32_16x16x32_bf16 v[36:39], v[160:163], v[204:207], v[36:39]
	v_mfma_f32_16x16x32_bf16 v[28:31], v[152:155], v[212:215], v[28:31]
	v_mfma_f32_16x16x32_bf16 v[20:23], v[160:163], v[212:215], v[20:23]
	v_mfma_f32_16x16x32_bf16 v[12:15], v[152:155], v[226:229], v[12:15]
	v_mfma_f32_16x16x32_bf16 v[4:7], v[160:163], v[226:229], v[4:7]
	s_setprio 0
	s_setprio 1
	v_mfma_f32_16x16x32_bf16 v[56:59], v[164:167], v[180:183], v[56:59]
	v_mfma_f32_16x16x32_bf16 v[48:51], v[172:175], v[180:183], v[48:51]
	v_mfma_f32_16x16x32_bf16 v[40:43], v[164:167], v[200:203], v[40:43]
	v_mfma_f32_16x16x32_bf16 v[32:35], v[172:175], v[200:203], v[32:35]
	v_mfma_f32_16x16x32_bf16 v[24:27], v[164:167], v[208:211], v[24:27]
	v_mfma_f32_16x16x32_bf16 v[16:19], v[172:175], v[208:211], v[16:19]
	v_mfma_f32_16x16x32_bf16 v[8:11], v[164:167], v[216:219], v[8:11]
	v_mfma_f32_16x16x32_bf16 v[0:3], v[172:175], v[216:219], v[0:3]
	v_mfma_f32_16x16x32_bf16 v[56:59], v[168:171], v[184:187], v[56:59]
	v_mfma_f32_16x16x32_bf16 v[48:51], v[176:179], v[184:187], v[48:51]
	v_mfma_f32_16x16x32_bf16 v[40:43], v[168:171], v[204:207], v[40:43]
	v_mfma_f32_16x16x32_bf16 v[32:35], v[176:179], v[204:207], v[32:35]
	v_mfma_f32_16x16x32_bf16 v[24:27], v[168:171], v[212:215], v[24:27]
	v_mfma_f32_16x16x32_bf16 v[16:19], v[176:179], v[212:215], v[16:19]
	v_mfma_f32_16x16x32_bf16 v[8:11], v[168:171], v[226:229], v[8:11]
	v_mfma_f32_16x16x32_bf16 v[0:3], v[176:179], v[226:229], v[0:3]
	s_setprio 0
	s_barrier
	s_add_i32 s57, s57, 2
	s_add_u32 s55, s55, 0x100
	s_addc_u32 s56, s56, 0
	s_add_u32 s2, s2, 0x100
	s_addc_u32 s3, s3, 0
	s_cmp_gt_u32 s57, 13
	s_cbranch_scc0 .LBB0_1385
	s_and_b64 vcc, exec, s[10:11]
	s_cbranch_vccz .LBB0_1388
	s_barrier

; #define PG8_STAGE(bufoff, gbase, voff) do { _Pragma("unroll") for (int _i = 0; _i < 2; ++_i) \
;         __builtin_amdgcn_global_load_lds((const unsigned*)((const char*)(gbase) + (voff)[_i]), (PG8_LAS unsigned*)(lds + (bufoff) + ldsw + _i * 8192), 16, 0, 0); } while (0)
; #define PG8_LDA(dst, b, h) do { _Pragma("unroll") for (int m = 0; m < 4; ++m) _Pragma("unroll") for (int k = 0; k < 2; ++k) dst[m][k] = *(const PG8_LAS bf16x8*)(lds + PG8_SA(b, h) + aoff + m * 2048 + k * 1024); } while (0)
; #define PG8_LDB(dst, b, h) do { _Pragma("unroll") for (int n = 0; n < 2; ++n) _Pragma("unroll") for (int k = 0; k < 2; ++k) dst[n][k] = *(const PG8_LAS bf16x8*)(lds + PG8_SB(b, h) + boff + n * 2048 + k * 1024); } while (0)
; #define PG8_MMA(ai, bj, At, Bt) do { __builtin_amdgcn_s_setprio(1); _Pragma("unroll") for (int m = 0; m < 4; ++m) _Pragma("unroll") for (int n = 0; n < 2; ++n) _Pragma("unroll") for (int k = 0; k < 2; ++k) \
;         acc[ai][bj][m][n] = __builtin_amdgcn_mfma_f32_16x16x32_bf16(Bt[n][k], At[m][k], acc[ai][bj][m][n], 0, 0, 0); __builtin_amdgcn_s_setprio(0); } while (0)
; #define PG8_WAIT_V(n) asm volatile("s_waitcnt vmcnt(" #n ")" ::: "memory")
; #define PG8_WAIT_L(n) asm volatile("s_waitcnt lgkmcnt(" #n ")" ::: "memory")
; #define PG8_BAR __builtin_amdgcn_s_barrier()
; #define PG8_SCHED __builtin_amdgcn_sched_barrier(0)
; template <class Epi, class Sched, bool ALIGN_EPI = false, bool SP2 = false>
; __device__ __forceinline__ void gemm_phase(PG8_LAS unsigned char* lds, const Gemm g, const Sched& S, const Epi& E, int tid_in) {
;     ...
;             const bool last = (t == nt - 2);
;             const char* a1 = cA + (size_t)(t + 1) * kstep;
;             const char* a2 = last ? nA : cA + (size_t)(t + 2) * kstep; const char* b2 = last ? nB : cB + (size_t)(t + 2) * kstep;
;             const char* a3 = a2 + kstep; const char* b3 = b2 + kstep;
;             if (last && has_next) S.a_ready(nxt);
;             if constexpr (SP2) {
;             PG8_LDB(B0, 0, 0); PG8_LDB(B1, 0, 1); PG8_SCHED; PG8_LDA(At, 0, 0); PG8_STAGE(PG8_SA(1, 1), a1 + hstepA, voffA);
;             PG8_WAIT_V(8); PG8_WAIT_L(0); PG8_BAR; PG8_MMA(0, 0, At, B0); PG8_MMA(0, 1, At, B1); PG8_BAR; PG8_SCHED;
;             PG8_LDA(At, 0, 1); PG8_STAGE(PG8_SB(0, 0), b2, voffB); PG8_STAGE(PG8_SB(0, 1), b2 + hstep, voffB); PG8_STAGE(PG8_SA(0, 0), a2, voffA);
.LBB0_1479:
	s_add_u32 s14, s12, 0x100
	s_addc_u32 s15, s13, 0
	s_add_i32 s56, 0, 0x10000
	s_cmp_eq_u32 s55, 40
	s_cselect_b32 s25, s11, s15
	s_cselect_b32 s24, s10, s14
	s_cselect_b32 s21, s19, s45
	s_cselect_b32 s20, s18, s44
	s_add_i32 s57, 0, 0x14000
	v_add_u32_e32 v124, s56, v226
	v_add_u32_e32 v140, s57, v226
	ds_read_b128 v[112:115], v124
	ds_read_b128 v[116:119], v124 offset:1024
	ds_read_b128 v[120:123], v124 offset:2048
	ds_read_b128 v[124:127], v124 offset:3072
	ds_read_b128 v[128:131], v140
	ds_read_b128 v[132:135], v140 offset:1024
	ds_read_b128 v[136:139], v140 offset:2048
	ds_read_b128 v[140:143], v140 offset:3072
	s_add_i32 m0, s31, 0xc000
	ds_read_b128 v[144:147], v227
	ds_read_b128 v[148:151], v227 offset:1024
	ds_read_b128 v[152:155], v227 offset:2048
	ds_read_b128 v[156:159], v227 offset:3072
	ds_read_b128 v[176:179], v227 offset:4096
	ds_read_b128 v[180:183], v227 offset:5120
	ds_read_b128 v[208:211], v227 offset:6144
	global_load_lds_dwordx4 v206, s[12:13]
	s_add_i32 m0, s31, 0xe000
	ds_read_b128 v[212:215], v227 offset:7168
	global_load_lds_dwordx4 v204, s[12:13]
	s_waitcnt vmcnt(8)
	s_waitcnt lgkmcnt(0)
	s_barrier
	s_setprio 1
	s_waitcnt lgkmcnt(0)
	v_mfma_f32_16x16x32_bf16 v[172:175], v[112:115], v[144:147], v[172:175]
	v_mfma_f32_16x16x32_bf16 v[168:171], v[120:123], v[144:147], v[168:171]
	v_mfma_f32_16x16x32_bf16 v[108:111], v[112:115], v[152:155], v[108:111]
	v_mfma_f32_16x16x32_bf16 v[104:107], v[120:123], v[152:155], v[104:107]
	v_mfma_f32_16x16x32_bf16 v[92:95], v[112:115], v[176:179], v[92:95]
	v_mfma_f32_16x16x32_bf16 v[88:91], v[120:123], v[176:179], v[88:91]
	v_mfma_f32_16x16x32_bf16 v[76:79], v[112:115], v[208:211], v[76:79]
	v_mfma_f32_16x16x32_bf16 v[72:75], v[120:123], v[208:211], v[72:75]
	v_mfma_f32_16x16x32_bf16 v[172:175], v[116:119], v[148:151], v[172:175]
	v_mfma_f32_16x16x32_bf16 v[168:171], v[124:127], v[148:151], v[168:171]
	v_mfma_f32_16x16x32_bf16 v[108:111], v[116:119], v[156:159], v[108:111]
	v_mfma_f32_16x16x32_bf16 v[104:107], v[124:127], v[156:159], v[104:107]
	v_mfma_f32_16x16x32_bf16 v[92:95], v[116:119], v[180:183], v[92:95]
	v_mfma_f32_16x16x32_bf16 v[88:91], v[124:127], v[180:183], v[88:91]
	v_mfma_f32_16x16x32_bf16 v[76:79], v[116:119], v[212:215], v[76:79]
	v_mfma_f32_16x16x32_bf16 v[72:75], v[124:127], v[212:215], v[72:75]
	s_setprio 0
	s_setprio 1
	v_mfma_f32_16x16x32_bf16 v[164:167], v[128:131], v[144:147], v[164:167]
	v_mfma_f32_16x16x32_bf16 v[100:103], v[128:131], v[152:155], v[100:103]
	v_mfma_f32_16x16x32_bf16 v[96:99], v[136:139], v[152:155], v[96:99]
	v_mfma_f32_16x16x32_bf16 v[84:87], v[128:131], v[176:179], v[84:87]
	v_mfma_f32_16x16x32_bf16 v[80:83], v[136:139], v[176:179], v[80:83]
	v_mfma_f32_16x16x32_bf16 v[68:71], v[128:131], v[208:211], v[68:71]
	v_mfma_f32_16x16x32_bf16 v[64:67], v[136:139], v[208:211], v[64:67]
	v_mfma_f32_16x16x32_bf16 v[164:167], v[132:135], v[148:151], v[164:167]
	v_mfma_f32_16x16x32_bf16 v[144:147], v[136:139], v[144:147], v[160:163]
	v_mfma_f32_16x16x32_bf16 v[100:103], v[132:135], v[156:159], v[100:103]
	v_mfma_f32_16x16x32_bf16 v[96:99], v[140:143], v[156:159], v[96:99]
	v_mfma_f32_16x16x32_bf16 v[84:87], v[132:135], v[180:183], v[84:87]
	v_mfma_f32_16x16x32_bf16 v[80:83], v[140:143], v[180:183], v[80:83]
	v_mfma_f32_16x16x32_bf16 v[68:71], v[132:135], v[212:215], v[68:71]
	v_mfma_f32_16x16x32_bf16 v[64:67], v[140:143], v[212:215], v[64:67]
	v_mfma_f32_16x16x32_bf16 v[144:147], v[140:143], v[148:151], v[144:147]
	s_setprio 0
	s_barrier
	s_add_i32 s12, s56, s30
	s_mov_b64 s[100:101], s[20:21]
	s_mov_b32 m0, s12
	ds_read_b128 v[148:151], v227 offset:16384
	ds_read_b128 v[152:155], v227 offset:17408
	ds_read_b128 v[156:159], v227 offset:18432
	ds_read_b128 v[160:163], v227 offset:19456
	ds_read_b128 v[176:179], v227 offset:20480
	ds_read_b128 v[180:183], v227 offset:21504
	global_load_lds_dwordx4 v190, s[100:101]
	s_add_i32 m0, s12, 0x2000
	s_add_u32 s12, s20, 0xb0000
	s_addc_u32 s13, s21, 0
	s_add_i32 s56, s57, s30
	global_load_lds_dwordx4 v184, s[100:101]
	s_mov_b32 m0, s56
	v_lshl_add_u64 v[232:233], s[24:25], 0, v[188:189]
	global_load_lds_dwordx4 v190, s[12:13]
	s_add_i32 m0, s56, 0x2000
	v_lshl_add_u64 v[234:235], s[24:25], 0, v[186:187]
	global_load_lds_dwordx4 v184, s[12:13]
	s_mov_b32 m0, s31
	ds_read_b128 v[208:211], v227 offset:22528
	global_load_lds_dwordx4 v[232:233], off
	s_mov_b32 m0, s34
	ds_read_b128 v[212:215], v227 offset:23552
	global_load_lds_dwordx4 v[234:235], off
	s_waitcnt vmcnt(8)
	s_waitcnt lgkmcnt(0)
	s_barrier
; #define PG8_STAGE(bufoff, gbase, voff) do { _Pragma("unroll") for (int _i = 0; _i < 2; ++_i) \
;         __builtin_amdgcn_global_load_lds((const unsigned*)((const char*)(gbase) + (voff)[_i]), (PG8_LAS unsigned*)(lds + (bufoff) + ldsw + _i * 8192), 16, 0, 0); } while (0)
; #define PG8_LDA(dst, b, h) do { _Pragma("unroll") for (int m = 0; m < 4; ++m) _Pragma("unroll") for (int k = 0; k < 2; ++k) dst[m][k] = *(const PG8_LAS bf16x8*)(lds + PG8_SA(b, h) + aoff + m * 2048 + k * 1024); } while (0)
; #define PG8_LDB(dst, b, h) do { _Pragma("unroll") for (int n = 0; n < 2; ++n) _Pragma("unroll") for (int k = 0; k < 2; ++k) dst[n][k] = *(const PG8_LAS bf16x8*)(lds + PG8_SB(b, h) + boff + n * 2048 + k * 1024); } while (0)
; #define PG8_MMA(ai, bj, At, Bt) do { __builtin_amdgcn_s_setprio(1); _Pragma("unroll") for (int m = 0; m < 4; ++m) _Pragma("unroll") for (int n = 0; n < 2; ++n) _Pragma("unroll") for (int k = 0; k < 2; ++k) \
;         acc[ai][bj][m][n] = __builtin_amdgcn_mfma_f32_16x16x32_bf16(Bt[n][k], At[m][k], acc[ai][bj][m][n], 0, 0, 0); __builtin_amdgcn_s_setprio(0); } while (0)
; #define PG8_WAIT_V(n) asm volatile("s_waitcnt vmcnt(" #n ")" ::: "memory")
; #define PG8_WAIT_L(n) asm volatile("s_waitcnt lgkmcnt(" #n ")" ::: "memory")
; #define PG8_BAR __builtin_amdgcn_s_barrier()
; #define PG8_SCHED __builtin_amdgcn_sched_barrier(0)
; template <class Epi, class Sched, bool ALIGN_EPI = false, bool SP2 = false>
; __device__ __forceinline__ void gemm_phase(PG8_LAS unsigned char* lds, const Gemm g, const Sched& S, const Epi& E, int tid_in) {
;     ...
;             PG8_WAIT_V(8); PG8_WAIT_L(0); PG8_BAR; PG8_MMA(1, 0, At, B0); PG8_MMA(1, 1, At, B1); PG8_BAR; PG8_SCHED;
;             PG8_LDB(B0, 1, 0); PG8_LDB(B1, 1, 1); PG8_SCHED; PG8_LDA(At, 1, 0); PG8_STAGE(PG8_SA(0, 1), a2 + hstepA, voffA);
;             PG8_WAIT_V(8); PG8_WAIT_L(0); PG8_BAR; PG8_MMA(0, 0, At, B0); PG8_MMA(0, 1, At, B1); PG8_BAR; PG8_SCHED;
	s_setprio 1
	s_waitcnt lgkmcnt(0)
	v_mfma_f32_16x16x32_bf16 v[60:63], v[112:115], v[148:151], v[60:63]
	v_mfma_f32_16x16x32_bf16 v[56:59], v[120:123], v[148:151], v[56:59]
	v_mfma_f32_16x16x32_bf16 v[44:47], v[112:115], v[156:159], v[44:47]
	v_mfma_f32_16x16x32_bf16 v[40:43], v[120:123], v[156:159], v[40:43]
	v_mfma_f32_16x16x32_bf16 v[28:31], v[112:115], v[176:179], v[28:31]
	v_mfma_f32_16x16x32_bf16 v[24:27], v[120:123], v[176:179], v[24:27]
	v_mfma_f32_16x16x32_bf16 v[12:15], v[112:115], v[208:211], v[12:15]
	v_mfma_f32_16x16x32_bf16 v[8:11], v[120:123], v[208:211], v[8:11]
	v_mfma_f32_16x16x32_bf16 v[60:63], v[116:119], v[152:155], v[60:63]
	v_mfma_f32_16x16x32_bf16 v[56:59], v[124:127], v[152:155], v[56:59]
	v_mfma_f32_16x16x32_bf16 v[44:47], v[116:119], v[160:163], v[44:47]
	v_mfma_f32_16x16x32_bf16 v[40:43], v[124:127], v[160:163], v[40:43]
	v_mfma_f32_16x16x32_bf16 v[28:31], v[116:119], v[180:183], v[28:31]
	v_mfma_f32_16x16x32_bf16 v[24:27], v[124:127], v[180:183], v[24:27]
	v_mfma_f32_16x16x32_bf16 v[12:15], v[116:119], v[212:215], v[12:15]
	v_mfma_f32_16x16x32_bf16 v[8:11], v[124:127], v[212:215], v[8:11]
	s_setprio 0
	s_setprio 1
	v_mfma_f32_16x16x32_bf16 v[52:55], v[128:131], v[148:151], v[52:55]
	v_mfma_f32_16x16x32_bf16 v[48:51], v[136:139], v[148:151], v[48:51]
	v_mfma_f32_16x16x32_bf16 v[36:39], v[128:131], v[156:159], v[36:39]
	v_mfma_f32_16x16x32_bf16 v[32:35], v[136:139], v[156:159], v[32:35]
	v_mfma_f32_16x16x32_bf16 v[20:23], v[128:131], v[176:179], v[20:23]
	v_mfma_f32_16x16x32_bf16 v[16:19], v[136:139], v[176:179], v[16:19]
	v_mfma_f32_16x16x32_bf16 v[4:7], v[128:131], v[208:211], v[4:7]
	v_mfma_f32_16x16x32_bf16 v[0:3], v[136:139], v[208:211], v[0:3]
	v_mfma_f32_16x16x32_bf16 v[52:55], v[132:135], v[152:155], v[52:55]
	v_mfma_f32_16x16x32_bf16 v[48:51], v[140:143], v[152:155], v[48:51]
	v_mfma_f32_16x16x32_bf16 v[36:39], v[132:135], v[160:163], v[36:39]
	v_mfma_f32_16x16x32_bf16 v[32:35], v[140:143], v[160:163], v[32:35]
	v_mfma_f32_16x16x32_bf16 v[20:23], v[132:135], v[180:183], v[20:23]
	v_mfma_f32_16x16x32_bf16 v[16:19], v[140:143], v[180:183], v[16:19]
	v_mfma_f32_16x16x32_bf16 v[4:7], v[132:135], v[212:215], v[4:7]
	v_mfma_f32_16x16x32_bf16 v[0:3], v[140:143], v[212:215], v[0:3]
	s_setprio 0
	s_barrier
	s_add_i32 s56, 0, 0x18000
	s_add_i32 s57, 0, 0x1c000
	v_add_u32_e32 v124, s56, v226
	v_add_u32_e32 v140, s57, v226
	ds_read_b128 v[112:115], v124
	ds_read_b128 v[116:119], v124 offset:1024
	ds_read_b128 v[120:123], v124 offset:2048
	ds_read_b128 v[124:127], v124 offset:3072
	ds_read_b128 v[128:131], v140
	ds_read_b128 v[132:135], v140 offset:1024
	ds_read_b128 v[136:139], v140 offset:2048
	ds_read_b128 v[140:143], v140 offset:3072
	s_add_u32 s12, s24, 0xb0000
	s_addc_u32 s13, s25, 0
	s_mov_b32 m0, s35
	ds_read_b128 v[148:151], v227 offset:32768
	ds_read_b128 v[152:155], v227 offset:33792
	ds_read_b128 v[156:159], v227 offset:34816
	ds_read_b128 v[176:179], v227 offset:35840
	ds_read_b128 v[180:183], v227 offset:36864
	ds_read_b128 v[208:211], v227 offset:37888
	ds_read_b128 v[212:215], v227 offset:38912
	global_load_lds_dwordx4 v188, s[12:13]
	s_mov_b32 m0, s46
	ds_read_b128 v[216:219], v227 offset:39936
	global_load_lds_dwordx4 v186, s[12:13]
	s_waitcnt vmcnt(8)
	s_waitcnt lgkmcnt(0)
	s_barrier
	s_setprio 1
	s_waitcnt lgkmcnt(0)
	v_mfma_f32_16x16x32_bf16 v[160:163], v[112:115], v[148:151], v[172:175]
	v_mfma_f32_16x16x32_bf16 v[172:175], v[116:119], v[152:155], v[160:163]
	v_mfma_f32_16x16x32_bf16 v[160:163], v[120:123], v[148:151], v[168:171]
	v_mfma_f32_16x16x32_bf16 v[108:111], v[112:115], v[156:159], v[108:111]
	v_mfma_f32_16x16x32_bf16 v[104:107], v[120:123], v[156:159], v[104:107]
	v_mfma_f32_16x16x32_bf16 v[92:95], v[112:115], v[180:183], v[92:95]
	v_mfma_f32_16x16x32_bf16 v[88:91], v[120:123], v[180:183], v[88:91]
	v_mfma_f32_16x16x32_bf16 v[76:79], v[112:115], v[212:215], v[76:79]
	v_mfma_f32_16x16x32_bf16 v[72:75], v[120:123], v[212:215], v[72:75]
	v_mfma_f32_16x16x32_bf16 v[168:171], v[124:127], v[152:155], v[160:163]
	v_mfma_f32_16x16x32_bf16 v[108:111], v[116:119], v[176:179], v[108:111]
	v_mfma_f32_16x16x32_bf16 v[104:107], v[124:127], v[176:179], v[104:107]
	v_mfma_f32_16x16x32_bf16 v[92:95], v[116:119], v[208:211], v[92:95]
	v_mfma_f32_16x16x32_bf16 v[88:91], v[124:127], v[208:211], v[88:91]
	v_mfma_f32_16x16x32_bf16 v[76:79], v[116:119], v[216:219], v[76:79]
	v_mfma_f32_16x16x32_bf16 v[72:75], v[124:127], v[216:219], v[72:75]
	s_setprio 0
	s_setprio 1
	v_mfma_f32_16x16x32_bf16 v[160:163], v[128:131], v[148:151], v[164:167]
	v_mfma_f32_16x16x32_bf16 v[144:147], v[136:139], v[148:151], v[144:147]
	v_mfma_f32_16x16x32_bf16 v[100:103], v[128:131], v[156:159], v[100:103]
	v_mfma_f32_16x16x32_bf16 v[96:99], v[136:139], v[156:159], v[96:99]
	v_mfma_f32_16x16x32_bf16 v[84:87], v[128:131], v[180:183], v[84:87]
	v_mfma_f32_16x16x32_bf16 v[80:83], v[136:139], v[180:183], v[80:83]
	v_mfma_f32_16x16x32_bf16 v[68:71], v[128:131], v[212:215], v[68:71]
	v_mfma_f32_16x16x32_bf16 v[64:67], v[136:139], v[212:215], v[64:67]
	v_mfma_f32_16x16x32_bf16 v[164:167], v[132:135], v[152:155], v[160:163]
	v_mfma_f32_16x16x32_bf16 v[160:163], v[140:143], v[152:155], v[144:147]
	v_mfma_f32_16x16x32_bf16 v[100:103], v[132:135], v[176:179], v[100:103]
	v_mfma_f32_16x16x32_bf16 v[96:99], v[140:143], v[176:179], v[96:99]
	v_mfma_f32_16x16x32_bf16 v[84:87], v[132:135], v[208:211], v[84:87]
	v_mfma_f32_16x16x32_bf16 v[80:83], v[140:143], v[208:211], v[80:83]
	v_mfma_f32_16x16x32_bf16 v[68:71], v[132:135], v[216:219], v[68:71]
	v_mfma_f32_16x16x32_bf16 v[64:67], v[140:143], v[216:219], v[64:67]
	s_setprio 0
	s_barrier
; #define PG8_STAGE(bufoff, gbase, voff) do { _Pragma("unroll") for (int _i = 0; _i < 2; ++_i) \
;         __builtin_amdgcn_global_load_lds((const unsigned*)((const char*)(gbase) + (voff)[_i]), (PG8_LAS unsigned*)(lds + (bufoff) + ldsw + _i * 8192), 16, 0, 0); } while (0)
; #define PG8_LDA(dst, b, h) do { _Pragma("unroll") for (int m = 0; m < 4; ++m) _Pragma("unroll") for (int k = 0; k < 2; ++k) dst[m][k] = *(const PG8_LAS bf16x8*)(lds + PG8_SA(b, h) + aoff + m * 2048 + k * 1024); } while (0)
; #define PG8_MMA(ai, bj, At, Bt) do { __builtin_amdgcn_s_setprio(1); _Pragma("unroll") for (int m = 0; m < 4; ++m) _Pragma("unroll") for (int n = 0; n < 2; ++n) _Pragma("unroll") for (int k = 0; k < 2; ++k) \
;         acc[ai][bj][m][n] = __builtin_amdgcn_mfma_f32_16x16x32_bf16(Bt[n][k], At[m][k], acc[ai][bj][m][n], 0, 0, 0); __builtin_amdgcn_s_setprio(0); } while (0)
; #define PG8_WAIT_V(n) asm volatile("s_waitcnt vmcnt(" #n ")" ::: "memory")
; #define PG8_WAIT_L(n) asm volatile("s_waitcnt lgkmcnt(" #n ")" ::: "memory")
; #define PG8_BAR __builtin_amdgcn_s_barrier()
; #define PG8_SCHED __builtin_amdgcn_sched_barrier(0)
; template <class Epi, class Sched, bool ALIGN_EPI = false, bool SP2 = false>
; __device__ __forceinline__ void gemm_phase(PG8_LAS unsigned char* lds, const Gemm g, const Sched& S, const Epi& E, int tid_in) {
;     ...
;             PG8_LDA(At, 1, 1); PG8_STAGE(PG8_SB(1, 0), b3, voffB); PG8_STAGE(PG8_SB(1, 1), b3 + hstep, voffB); PG8_STAGE(PG8_SA(1, 0), a3, voffA);
;             PG8_WAIT_V(8); PG8_WAIT_L(0); PG8_BAR; PG8_MMA(1, 0, At, B0); PG8_MMA(1, 1, At, B1); PG8_BAR; PG8_SCHED;
	s_add_i32 s12, s56, s30
	s_mov_b32 m0, s12
	ds_read_b128 v[144:147], v227 offset:49152
	ds_read_b128 v[148:151], v227 offset:50176
	ds_read_b128 v[152:155], v227 offset:51200
	ds_read_b128 v[156:159], v227 offset:52224
	s_add_u32 s100, s100, 0x80
	s_addc_u32 s101, s101, 0
	global_load_lds_dwordx4 v190, s[100:101]
	s_add_i32 m0, s12, 0x2000
	s_add_u32 s12, s20, 0xb0080
	s_addc_u32 s13, s21, 0
	s_add_i32 s20, s57, s30
	global_load_lds_dwordx4 v184, s[100:101]
	s_mov_b32 m0, s20
	ds_read_b128 v[176:179], v227 offset:53248
	global_load_lds_dwordx4 v190, s[12:13]
	s_add_i32 m0, s20, 0x2000
	ds_read_b128 v[180:183], v227 offset:54272
	global_load_lds_dwordx4 v184, s[12:13]
	v_lshl_add_u64 v[216:217], v[232:233], 0, s[0:1]
	s_mov_b32 m0, s49
	ds_read_b128 v[208:211], v227 offset:55296
	global_load_lds_dwordx4 v[216:217], off
	v_lshl_add_u64 v[216:217], v[234:235], 0, s[0:1]
	s_mov_b32 m0, s50
	ds_read_b128 v[212:215], v227 offset:56320
	global_load_lds_dwordx4 v[216:217], off
	s_waitcnt vmcnt(8)
	s_waitcnt lgkmcnt(0)
	s_barrier
	s_setprio 1
	s_waitcnt lgkmcnt(0)
	v_mfma_f32_16x16x32_bf16 v[60:63], v[112:115], v[144:147], v[60:63]
	v_mfma_f32_16x16x32_bf16 v[56:59], v[120:123], v[144:147], v[56:59]
	v_mfma_f32_16x16x32_bf16 v[44:47], v[112:115], v[152:155], v[44:47]
	v_mfma_f32_16x16x32_bf16 v[40:43], v[120:123], v[152:155], v[40:43]
	v_mfma_f32_16x16x32_bf16 v[28:31], v[112:115], v[176:179], v[28:31]
	v_mfma_f32_16x16x32_bf16 v[24:27], v[120:123], v[176:179], v[24:27]
	v_mfma_f32_16x16x32_bf16 v[12:15], v[112:115], v[208:211], v[12:15]
	v_mfma_f32_16x16x32_bf16 v[8:11], v[120:123], v[208:211], v[8:11]
	v_mfma_f32_16x16x32_bf16 v[60:63], v[116:119], v[148:151], v[60:63]
	v_mfma_f32_16x16x32_bf16 v[56:59], v[124:127], v[148:151], v[56:59]
	v_mfma_f32_16x16x32_bf16 v[44:47], v[116:119], v[156:159], v[44:47]
	v_mfma_f32_16x16x32_bf16 v[40:43], v[124:127], v[156:159], v[40:43]
	v_mfma_f32_16x16x32_bf16 v[28:31], v[116:119], v[180:183], v[28:31]
	v_mfma_f32_16x16x32_bf16 v[24:27], v[124:127], v[180:183], v[24:27]
	v_mfma_f32_16x16x32_bf16 v[12:15], v[116:119], v[212:215], v[12:15]
	v_mfma_f32_16x16x32_bf16 v[8:11], v[124:127], v[212:215], v[8:11]
	s_setprio 0
	s_setprio 1
	v_mfma_f32_16x16x32_bf16 v[52:55], v[128:131], v[144:147], v[52:55]
	v_mfma_f32_16x16x32_bf16 v[48:51], v[136:139], v[144:147], v[48:51]
	v_mfma_f32_16x16x32_bf16 v[36:39], v[128:131], v[152:155], v[36:39]
	v_mfma_f32_16x16x32_bf16 v[32:35], v[136:139], v[152:155], v[32:35]
	v_mfma_f32_16x16x32_bf16 v[20:23], v[128:131], v[176:179], v[20:23]
	v_mfma_f32_16x16x32_bf16 v[16:19], v[136:139], v[176:179], v[16:19]
	v_mfma_f32_16x16x32_bf16 v[4:7], v[128:131], v[208:211], v[4:7]
	v_mfma_f32_16x16x32_bf16 v[0:3], v[136:139], v[208:211], v[0:3]
	v_mfma_f32_16x16x32_bf16 v[52:55], v[132:135], v[148:151], v[52:55]
	v_mfma_f32_16x16x32_bf16 v[48:51], v[140:143], v[148:151], v[48:51]
	v_mfma_f32_16x16x32_bf16 v[36:39], v[132:135], v[156:159], v[36:39]
	v_mfma_f32_16x16x32_bf16 v[32:35], v[140:143], v[156:159], v[32:35]
	v_mfma_f32_16x16x32_bf16 v[20:23], v[132:135], v[180:183], v[20:23]
	v_mfma_f32_16x16x32_bf16 v[16:19], v[140:143], v[180:183], v[16:19]
	v_mfma_f32_16x16x32_bf16 v[4:7], v[132:135], v[212:215], v[4:7]
	v_mfma_f32_16x16x32_bf16 v[0:3], v[140:143], v[212:215], v[0:3]
	s_setprio 0
	s_barrier
	s_add_i32 s55, s55, 2
	s_add_u32 s44, s44, 0x100
	s_addc_u32 s45, s45, 0
	s_cmp_gt_u32 s55, 41
	s_mov_b64 s[12:13], s[14:15]
	s_cbranch_scc0 .LBB0_1479
	s_and_b64 vcc, exec, s[8:9]
	s_cbranch_vccz .LBB0_1482
	s_barrier
